# SGPR-base LDS-DMA addressing in P2/P8 K-loops (no VALU addr, no s_nop) + hoisted/counted-wait loads in P6 step-1 and P9 final-norm epilogues
# speedup vs baseline: 1.0294x; 1.0294x over previous
.LBB0_156:
	s_ashr_i32 s65, s64, 31
	s_lshl_b64 s[34:35], s[64:65], 20
	s_add_u32 s66, s33, s34
	s_addc_u32 s67, s38, s35
	s_and_b64 s[34:35], s[72:73], exec
	s_cselect_b32 s2, s67, s9
	s_cselect_b32 s13, s66, s8
	s_ashr_i32 s63, s62, 31
	s_lshl_b64 s[34:35], s[62:63], 20
	s_add_u32 s68, s36, s34
	s_addc_u32 s69, s37, s35
	s_and_b64 s[34:35], s[72:73], exec
	s_cselect_b32 s20, s69, s11
	s_cselect_b32 s63, s68, s10
	s_add_u32 s8, s8, 0x80080
	s_addc_u32 s9, s9, 0
	s_add_u32 s65, s10, 0x100
	v_mov_b32_e32 v0, 0
	s_addc_u32 s71, s11, 0
	s_mov_b32 s74, -2
	v_mov_b32_e32 v1, v0
	v_mov_b32_e32 v2, v0
	v_mov_b32_e32 v3, v0
	v_mov_b32_e32 v4, v0
	v_mov_b32_e32 v5, v0
	v_mov_b32_e32 v6, v0
	v_mov_b32_e32 v7, v0
	v_mov_b32_e32 v16, v0
	v_mov_b32_e32 v17, v0
	v_mov_b32_e32 v18, v0
	v_mov_b32_e32 v19, v0
	v_mov_b32_e32 v20, v0
	v_mov_b32_e32 v21, v0
	v_mov_b32_e32 v22, v0
	v_mov_b32_e32 v23, v0
	v_mov_b32_e32 v32, v0
	v_mov_b32_e32 v33, v0
	v_mov_b32_e32 v34, v0
	v_mov_b32_e32 v35, v0
	v_mov_b32_e32 v36, v0
	v_mov_b32_e32 v37, v0
	v_mov_b32_e32 v38, v0
	v_mov_b32_e32 v39, v0
	v_mov_b32_e32 v48, v0
	v_mov_b32_e32 v49, v0
	v_mov_b32_e32 v50, v0
	v_mov_b32_e32 v51, v0
	v_mov_b32_e32 v52, v0
	v_mov_b32_e32 v53, v0
	v_mov_b32_e32 v54, v0
	v_mov_b32_e32 v55, v0
	v_mov_b32_e32 v8, v0
	v_mov_b32_e32 v9, v0
	v_mov_b32_e32 v10, v0
	v_mov_b32_e32 v11, v0
	v_mov_b32_e32 v12, v0
	v_mov_b32_e32 v13, v0
	v_mov_b32_e32 v14, v0
	v_mov_b32_e32 v15, v0
	v_mov_b32_e32 v24, v0
	v_mov_b32_e32 v25, v0
	v_mov_b32_e32 v26, v0
	v_mov_b32_e32 v27, v0
	v_mov_b32_e32 v28, v0
	v_mov_b32_e32 v29, v0
	v_mov_b32_e32 v30, v0
	v_mov_b32_e32 v31, v0
	v_mov_b32_e32 v40, v0
	v_mov_b32_e32 v41, v0
	v_mov_b32_e32 v42, v0
	v_mov_b32_e32 v43, v0
	v_mov_b32_e32 v44, v0
	v_mov_b32_e32 v45, v0
	v_mov_b32_e32 v46, v0
	v_mov_b32_e32 v47, v0
	v_mov_b32_e32 v56, v0
	v_mov_b32_e32 v57, v0
	v_mov_b32_e32 v58, v0
	v_mov_b32_e32 v59, v0
	v_mov_b32_e32 v60, v0
	v_mov_b32_e32 v61, v0
	v_mov_b32_e32 v62, v0
	v_mov_b32_e32 v63, v0
	v_mov_b32_e32 v64, v0
	v_mov_b32_e32 v65, v0
	v_mov_b32_e32 v66, v0
	v_mov_b32_e32 v67, v0
	v_mov_b32_e32 v68, v0
	v_mov_b32_e32 v69, v0
	v_mov_b32_e32 v70, v0
	v_mov_b32_e32 v71, v0
	v_mov_b32_e32 v80, v0
	v_mov_b32_e32 v81, v0
	v_mov_b32_e32 v82, v0
	v_mov_b32_e32 v83, v0
	v_mov_b32_e32 v84, v0
	v_mov_b32_e32 v85, v0
	v_mov_b32_e32 v86, v0
	v_mov_b32_e32 v87, v0
	v_mov_b32_e32 v96, v0
	v_mov_b32_e32 v97, v0
	v_mov_b32_e32 v98, v0
	v_mov_b32_e32 v99, v0
	v_mov_b32_e32 v100, v0
	v_mov_b32_e32 v101, v0
	v_mov_b32_e32 v102, v0
	v_mov_b32_e32 v103, v0
	v_mov_b32_e32 v112, v0
	v_mov_b32_e32 v113, v0
	v_mov_b32_e32 v114, v0
	v_mov_b32_e32 v115, v0
	v_mov_b32_e32 v116, v0
	v_mov_b32_e32 v117, v0
	v_mov_b32_e32 v118, v0
	v_mov_b32_e32 v119, v0
	v_mov_b32_e32 v72, v0
	v_mov_b32_e32 v73, v0
	v_mov_b32_e32 v74, v0
	v_mov_b32_e32 v75, v0
	v_mov_b32_e32 v76, v0
	v_mov_b32_e32 v77, v0
	v_mov_b32_e32 v78, v0
	v_mov_b32_e32 v79, v0
	v_mov_b32_e32 v88, v0
	v_mov_b32_e32 v89, v0
	v_mov_b32_e32 v90, v0
	v_mov_b32_e32 v91, v0
	v_mov_b32_e32 v92, v0
	v_mov_b32_e32 v93, v0
	v_mov_b32_e32 v94, v0
	v_mov_b32_e32 v95, v0
	v_mov_b32_e32 v104, v0
	v_mov_b32_e32 v105, v0
	v_mov_b32_e32 v106, v0
	v_mov_b32_e32 v107, v0
	v_mov_b32_e32 v108, v0
	v_mov_b32_e32 v109, v0
	v_mov_b32_e32 v110, v0
	v_mov_b32_e32 v111, v0
	v_mov_b32_e32 v120, v0
	v_mov_b32_e32 v121, v0
	v_mov_b32_e32 v122, v0
	v_mov_b32_e32 v123, v0
	v_mov_b32_e32 v124, v0
	v_mov_b32_e32 v125, v0
	v_mov_b32_e32 v126, v0
	v_mov_b32_e32 v127, v0
	.p2align 6
.LBB0_157:
	v_add_u32_e32 v140, s91, v180
	ds_read_b128 v[128:131], v140
	ds_read_b128 v[132:135], v140 offset:1024
	ds_read_b128 v[136:139], v140 offset:2048
	ds_read_b128 v[140:143], v140 offset:3072
	s_add_u32 s10, s8, 0xfff80080
	s_addc_u32 s11, s9, -1
	s_cmp_eq_u32 s74, 28
	s_cselect_b32 s73, s2, s11
	s_cselect_b32 s72, s13, s10
	s_cselect_b32 s11, s20, s71
	s_cselect_b32 s10, s63, s65
	s_add_i32 m0, s40, 0xc000
	ds_read_b128 v[144:147], v208
	ds_read_b128 v[172:175], v208 offset:1024
	ds_read_b128 v[176:179], v208 offset:2048
	ds_read_b128 v[212:215], v208 offset:3072
	global_load_lds_dwordx4 v166, s[8:9]
	s_add_i32 m0, s40, 0xe000
	ds_read_b128 v[216:219], v208 offset:4096
	ds_read_b128 v[220:223], v208 offset:5120
	ds_read_b128 v[224:227], v208 offset:6144
	ds_read_b128 v[228:231], v208 offset:7168
	global_load_lds_dwordx4 v168, s[8:9]
	s_waitcnt lgkmcnt(8)
	s_barrier
	s_waitcnt lgkmcnt(0)
	s_setprio 1
	v_mfma_f32_16x16x32_bf16 v[124:127], v[128:131], v[144:147], v[124:127]
	v_mfma_f32_16x16x32_bf16 v[120:123], v[136:139], v[144:147], v[120:123]
	v_mfma_f32_16x16x32_bf16 v[108:111], v[128:131], v[176:179], v[108:111]
	v_mfma_f32_16x16x32_bf16 v[104:107], v[136:139], v[176:179], v[104:107]
	v_mfma_f32_16x16x32_bf16 v[92:95], v[128:131], v[216:219], v[92:95]
	v_mfma_f32_16x16x32_bf16 v[88:91], v[136:139], v[216:219], v[88:91]
	v_mfma_f32_16x16x32_bf16 v[76:79], v[128:131], v[224:227], v[76:79]
	v_mfma_f32_16x16x32_bf16 v[72:75], v[136:139], v[224:227], v[72:75]
	v_mfma_f32_16x16x32_bf16 v[124:127], v[132:135], v[172:175], v[124:127]
	v_mfma_f32_16x16x32_bf16 v[120:123], v[140:143], v[172:175], v[120:123]
	v_mfma_f32_16x16x32_bf16 v[108:111], v[132:135], v[212:215], v[108:111]
	v_mfma_f32_16x16x32_bf16 v[104:107], v[140:143], v[212:215], v[104:107]
	v_mfma_f32_16x16x32_bf16 v[92:95], v[132:135], v[220:223], v[92:95]
	v_mfma_f32_16x16x32_bf16 v[88:91], v[140:143], v[220:223], v[88:91]
	v_mfma_f32_16x16x32_bf16 v[76:79], v[132:135], v[228:231], v[76:79]
	v_mfma_f32_16x16x32_bf16 v[72:75], v[140:143], v[228:231], v[72:75]
	s_setprio 0
	s_barrier
	v_add_u32_e32 v156, s92, v180
	s_add_i32 m0, s40, 0x10000
	ds_read_b128 v[232:235], v156
	ds_read_b128 v[236:239], v156 offset:1024
	global_load_lds_dwordx4 v150, s[10:11]
	s_add_i32 m0, s40, 0x12000
	ds_read_b128 v[240:243], v156 offset:2048
	ds_read_b128 v[244:247], v156 offset:3072
	global_load_lds_dwordx4 v154, s[10:11]
	s_barrier
	s_waitcnt lgkmcnt(0)
	s_setprio 1
	v_mfma_f32_16x16x32_bf16 v[116:119], v[232:235], v[144:147], v[116:119]
	v_mfma_f32_16x16x32_bf16 v[112:115], v[240:243], v[144:147], v[112:115]
	v_mfma_f32_16x16x32_bf16 v[100:103], v[232:235], v[176:179], v[100:103]
	v_mfma_f32_16x16x32_bf16 v[96:99], v[240:243], v[176:179], v[96:99]
	v_mfma_f32_16x16x32_bf16 v[84:87], v[232:235], v[216:219], v[84:87]
	v_mfma_f32_16x16x32_bf16 v[80:83], v[240:243], v[216:219], v[80:83]
	v_mfma_f32_16x16x32_bf16 v[68:71], v[232:235], v[224:227], v[68:71]
	v_mfma_f32_16x16x32_bf16 v[64:67], v[240:243], v[224:227], v[64:67]
	v_mfma_f32_16x16x32_bf16 v[116:119], v[236:239], v[172:175], v[116:119]
	v_mfma_f32_16x16x32_bf16 v[112:115], v[244:247], v[172:175], v[112:115]
	v_mfma_f32_16x16x32_bf16 v[100:103], v[236:239], v[212:215], v[100:103]
	v_mfma_f32_16x16x32_bf16 v[96:99], v[244:247], v[212:215], v[96:99]
	v_mfma_f32_16x16x32_bf16 v[84:87], v[236:239], v[220:223], v[84:87]
	v_mfma_f32_16x16x32_bf16 v[80:83], v[244:247], v[220:223], v[80:83]
	v_mfma_f32_16x16x32_bf16 v[68:71], v[236:239], v[228:231], v[68:71]
	v_mfma_f32_16x16x32_bf16 v[64:67], v[244:247], v[228:231], v[64:67]
	s_setprio 0
	s_barrier
	s_mov_b32 m0, s40
	ds_read_b128 v[144:147], v208 offset:16384
	ds_read_b128 v[172:175], v208 offset:17408
	ds_read_b128 v[176:179], v208 offset:18432
	ds_read_b128 v[212:215], v208 offset:19456
	global_load_lds_dwordx4 v148, s[72:73]
	s_mov_b32 m0, s41
	ds_read_b128 v[216:219], v208 offset:20480
	ds_read_b128 v[220:223], v208 offset:21504
	ds_read_b128 v[224:227], v208 offset:22528
	ds_read_b128 v[228:231], v208 offset:23552
	global_load_lds_dwordx4 v152, s[72:73]
	s_barrier
	s_waitcnt lgkmcnt(0)
	s_setprio 1
	v_mfma_f32_16x16x32_bf16 v[60:63], v[128:131], v[144:147], v[60:63]
	v_mfma_f32_16x16x32_bf16 v[56:59], v[136:139], v[144:147], v[56:59]
	v_mfma_f32_16x16x32_bf16 v[44:47], v[128:131], v[176:179], v[44:47]
	v_mfma_f32_16x16x32_bf16 v[40:43], v[136:139], v[176:179], v[40:43]
	v_mfma_f32_16x16x32_bf16 v[28:31], v[128:131], v[216:219], v[28:31]
	v_mfma_f32_16x16x32_bf16 v[24:27], v[136:139], v[216:219], v[24:27]
	v_mfma_f32_16x16x32_bf16 v[12:15], v[128:131], v[224:227], v[12:15]
	v_mfma_f32_16x16x32_bf16 v[8:11], v[136:139], v[224:227], v[8:11]
	v_mfma_f32_16x16x32_bf16 v[60:63], v[132:135], v[172:175], v[60:63]
	v_mfma_f32_16x16x32_bf16 v[56:59], v[140:143], v[172:175], v[56:59]
	v_mfma_f32_16x16x32_bf16 v[44:47], v[132:135], v[212:215], v[44:47]
	v_mfma_f32_16x16x32_bf16 v[40:43], v[140:143], v[212:215], v[40:43]
	v_mfma_f32_16x16x32_bf16 v[28:31], v[132:135], v[220:223], v[28:31]
	v_mfma_f32_16x16x32_bf16 v[24:27], v[140:143], v[220:223], v[24:27]
	v_mfma_f32_16x16x32_bf16 v[12:15], v[132:135], v[228:231], v[12:15]
	v_mfma_f32_16x16x32_bf16 v[8:11], v[140:143], v[228:231], v[8:11]
	s_setprio 0
	s_barrier
	s_add_u32 s34, s10, 0x80000
	s_addc_u32 s35, s11, 0
	s_add_i32 m0, s40, 0x14000
	s_nop 0
	global_load_lds_dwordx4 v150, s[34:35]
	s_add_i32 m0, s40, 0x16000
	s_nop 0
	global_load_lds_dwordx4 v154, s[34:35]
	s_waitcnt vmcnt(6)
	s_barrier
	s_setprio 1
	v_mfma_f32_16x16x32_bf16 v[52:55], v[232:235], v[144:147], v[52:55]
	v_mfma_f32_16x16x32_bf16 v[48:51], v[240:243], v[144:147], v[48:51]
	v_mfma_f32_16x16x32_bf16 v[36:39], v[232:235], v[176:179], v[36:39]
	v_mfma_f32_16x16x32_bf16 v[32:35], v[240:243], v[176:179], v[32:35]
	v_mfma_f32_16x16x32_bf16 v[20:23], v[232:235], v[216:219], v[20:23]
	v_mfma_f32_16x16x32_bf16 v[16:19], v[240:243], v[216:219], v[16:19]
	v_mfma_f32_16x16x32_bf16 v[4:7], v[232:235], v[224:227], v[4:7]
	v_mfma_f32_16x16x32_bf16 v[0:3], v[240:243], v[224:227], v[0:3]
	v_mfma_f32_16x16x32_bf16 v[52:55], v[236:239], v[172:175], v[52:55]
	v_mfma_f32_16x16x32_bf16 v[48:51], v[244:247], v[172:175], v[48:51]
	v_mfma_f32_16x16x32_bf16 v[36:39], v[236:239], v[212:215], v[36:39]
	v_mfma_f32_16x16x32_bf16 v[32:35], v[244:247], v[212:215], v[32:35]
	v_mfma_f32_16x16x32_bf16 v[20:23], v[236:239], v[220:223], v[20:23]
	v_mfma_f32_16x16x32_bf16 v[16:19], v[244:247], v[220:223], v[16:19]
	v_mfma_f32_16x16x32_bf16 v[4:7], v[236:239], v[228:231], v[4:7]
	v_mfma_f32_16x16x32_bf16 v[0:3], v[244:247], v[228:231], v[0:3]
	s_setprio 0
	s_barrier
	s_add_i32 s75, 0, 0x18000
	v_add_u32_e32 v140, s75, v180
	ds_read_b128 v[128:131], v140
	ds_read_b128 v[132:135], v140 offset:1024
	ds_read_b128 v[136:139], v140 offset:2048
	ds_read_b128 v[140:143], v140 offset:3072
	s_add_u32 s34, s72, 0x80000
	s_addc_u32 s35, s73, 0
	s_mov_b32 m0, s82
	ds_read_b128 v[144:147], v208 offset:32768
	ds_read_b128 v[172:175], v208 offset:33792
	ds_read_b128 v[176:179], v208 offset:34816
	ds_read_b128 v[212:215], v208 offset:35840
	global_load_lds_dwordx4 v148, s[34:35]
	s_mov_b32 m0, s83
	ds_read_b128 v[216:219], v208 offset:36864
	ds_read_b128 v[220:223], v208 offset:37888
	ds_read_b128 v[224:227], v208 offset:38912
	ds_read_b128 v[228:231], v208 offset:39936
	global_load_lds_dwordx4 v152, s[34:35]
	s_waitcnt lgkmcnt(8)
	s_barrier
	s_waitcnt lgkmcnt(0)
	s_setprio 1
	v_mfma_f32_16x16x32_bf16 v[124:127], v[128:131], v[144:147], v[124:127]
	v_mfma_f32_16x16x32_bf16 v[120:123], v[136:139], v[144:147], v[120:123]
	v_mfma_f32_16x16x32_bf16 v[108:111], v[128:131], v[176:179], v[108:111]
	v_mfma_f32_16x16x32_bf16 v[104:107], v[136:139], v[176:179], v[104:107]
	v_mfma_f32_16x16x32_bf16 v[92:95], v[128:131], v[216:219], v[92:95]
	v_mfma_f32_16x16x32_bf16 v[88:91], v[136:139], v[216:219], v[88:91]
	v_mfma_f32_16x16x32_bf16 v[76:79], v[128:131], v[224:227], v[76:79]
	v_mfma_f32_16x16x32_bf16 v[72:75], v[136:139], v[224:227], v[72:75]
	v_mfma_f32_16x16x32_bf16 v[124:127], v[132:135], v[172:175], v[124:127]
	v_mfma_f32_16x16x32_bf16 v[120:123], v[140:143], v[172:175], v[120:123]
	v_mfma_f32_16x16x32_bf16 v[108:111], v[132:135], v[212:215], v[108:111]
	v_mfma_f32_16x16x32_bf16 v[104:107], v[140:143], v[212:215], v[104:107]
	v_mfma_f32_16x16x32_bf16 v[92:95], v[132:135], v[220:223], v[92:95]
	v_mfma_f32_16x16x32_bf16 v[88:91], v[140:143], v[220:223], v[88:91]
	v_mfma_f32_16x16x32_bf16 v[76:79], v[132:135], v[228:231], v[76:79]
	v_mfma_f32_16x16x32_bf16 v[72:75], v[140:143], v[228:231], v[72:75]
	s_setprio 0
	s_barrier
	s_add_i32 s34, 0, 0x1c000
	v_add_u32_e32 v156, s34, v180
	s_add_u32 s34, s10, 0x80
	s_addc_u32 s35, s11, 0
	s_add_i32 m0, s40, 0x18000
	ds_read_b128 v[232:235], v156
	ds_read_b128 v[236:239], v156 offset:1024
	global_load_lds_dwordx4 v150, s[34:35]
	s_add_i32 m0, s40, 0x1a000
	ds_read_b128 v[240:243], v156 offset:2048
	ds_read_b128 v[244:247], v156 offset:3072
	global_load_lds_dwordx4 v154, s[34:35]
	s_barrier
	s_waitcnt lgkmcnt(0)
	s_setprio 1
	v_mfma_f32_16x16x32_bf16 v[116:119], v[232:235], v[144:147], v[116:119]
	v_mfma_f32_16x16x32_bf16 v[112:115], v[240:243], v[144:147], v[112:115]
	v_mfma_f32_16x16x32_bf16 v[100:103], v[232:235], v[176:179], v[100:103]
	v_mfma_f32_16x16x32_bf16 v[96:99], v[240:243], v[176:179], v[96:99]
	v_mfma_f32_16x16x32_bf16 v[84:87], v[232:235], v[216:219], v[84:87]
	v_mfma_f32_16x16x32_bf16 v[80:83], v[240:243], v[216:219], v[80:83]
	v_mfma_f32_16x16x32_bf16 v[68:71], v[232:235], v[224:227], v[68:71]
	v_mfma_f32_16x16x32_bf16 v[64:67], v[240:243], v[224:227], v[64:67]
	v_mfma_f32_16x16x32_bf16 v[116:119], v[236:239], v[172:175], v[116:119]
	v_mfma_f32_16x16x32_bf16 v[112:115], v[244:247], v[172:175], v[112:115]
	v_mfma_f32_16x16x32_bf16 v[100:103], v[236:239], v[212:215], v[100:103]
	v_mfma_f32_16x16x32_bf16 v[96:99], v[244:247], v[212:215], v[96:99]
	v_mfma_f32_16x16x32_bf16 v[84:87], v[236:239], v[220:223], v[84:87]
	v_mfma_f32_16x16x32_bf16 v[80:83], v[244:247], v[220:223], v[80:83]
	v_mfma_f32_16x16x32_bf16 v[68:71], v[236:239], v[228:231], v[68:71]
	v_mfma_f32_16x16x32_bf16 v[64:67], v[244:247], v[228:231], v[64:67]
	s_setprio 0
	s_barrier
	s_add_u32 s34, s72, 0x80
	s_addc_u32 s35, s73, 0
	s_mov_b32 m0, s87
	ds_read_b128 v[144:147], v208 offset:49152
	ds_read_b128 v[172:175], v208 offset:50176
	ds_read_b128 v[176:179], v208 offset:51200
	ds_read_b128 v[212:215], v208 offset:52224
	global_load_lds_dwordx4 v148, s[34:35]
	s_mov_b32 m0, s88
	ds_read_b128 v[216:219], v208 offset:53248
	ds_read_b128 v[220:223], v208 offset:54272
	ds_read_b128 v[224:227], v208 offset:55296
	ds_read_b128 v[228:231], v208 offset:56320
	global_load_lds_dwordx4 v152, s[34:35]
	s_barrier
	s_waitcnt lgkmcnt(0)
	s_setprio 1
	v_mfma_f32_16x16x32_bf16 v[60:63], v[128:131], v[144:147], v[60:63]
	v_mfma_f32_16x16x32_bf16 v[56:59], v[136:139], v[144:147], v[56:59]
	v_mfma_f32_16x16x32_bf16 v[44:47], v[128:131], v[176:179], v[44:47]
	v_mfma_f32_16x16x32_bf16 v[40:43], v[136:139], v[176:179], v[40:43]
	v_mfma_f32_16x16x32_bf16 v[28:31], v[128:131], v[216:219], v[28:31]
	v_mfma_f32_16x16x32_bf16 v[24:27], v[136:139], v[216:219], v[24:27]
	v_mfma_f32_16x16x32_bf16 v[12:15], v[128:131], v[224:227], v[12:15]
	v_mfma_f32_16x16x32_bf16 v[8:11], v[136:139], v[224:227], v[8:11]
	v_mfma_f32_16x16x32_bf16 v[60:63], v[132:135], v[172:175], v[60:63]
	v_mfma_f32_16x16x32_bf16 v[56:59], v[140:143], v[172:175], v[56:59]
	v_mfma_f32_16x16x32_bf16 v[44:47], v[132:135], v[212:215], v[44:47]
	v_mfma_f32_16x16x32_bf16 v[40:43], v[140:143], v[212:215], v[40:43]
	v_mfma_f32_16x16x32_bf16 v[28:31], v[132:135], v[220:223], v[28:31]
	v_mfma_f32_16x16x32_bf16 v[24:27], v[140:143], v[220:223], v[24:27]
	v_mfma_f32_16x16x32_bf16 v[12:15], v[132:135], v[228:231], v[12:15]
	v_mfma_f32_16x16x32_bf16 v[8:11], v[140:143], v[228:231], v[8:11]
	s_setprio 0
	s_barrier
	s_add_u32 s34, s10, 0x80080
	s_addc_u32 s35, s11, 0
	s_add_i32 m0, s40, 0x1c000
	s_nop 0
	global_load_lds_dwordx4 v150, s[34:35]
	s_add_i32 m0, s40, 0x1e000
	s_nop 0
	global_load_lds_dwordx4 v154, s[34:35]
	s_waitcnt vmcnt(6)
	s_barrier
	s_setprio 1
	v_mfma_f32_16x16x32_bf16 v[52:55], v[232:235], v[144:147], v[52:55]
	v_mfma_f32_16x16x32_bf16 v[48:51], v[240:243], v[144:147], v[48:51]
	v_mfma_f32_16x16x32_bf16 v[36:39], v[232:235], v[176:179], v[36:39]
	v_mfma_f32_16x16x32_bf16 v[32:35], v[240:243], v[176:179], v[32:35]
	v_mfma_f32_16x16x32_bf16 v[20:23], v[232:235], v[216:219], v[20:23]
	v_mfma_f32_16x16x32_bf16 v[16:19], v[240:243], v[216:219], v[16:19]
	v_mfma_f32_16x16x32_bf16 v[4:7], v[232:235], v[224:227], v[4:7]
	v_mfma_f32_16x16x32_bf16 v[0:3], v[240:243], v[224:227], v[0:3]
	v_mfma_f32_16x16x32_bf16 v[52:55], v[236:239], v[172:175], v[52:55]
	v_mfma_f32_16x16x32_bf16 v[48:51], v[244:247], v[172:175], v[48:51]
	v_mfma_f32_16x16x32_bf16 v[36:39], v[236:239], v[212:215], v[36:39]
	v_mfma_f32_16x16x32_bf16 v[32:35], v[244:247], v[212:215], v[32:35]
	v_mfma_f32_16x16x32_bf16 v[20:23], v[236:239], v[220:223], v[20:23]
	v_mfma_f32_16x16x32_bf16 v[16:19], v[244:247], v[220:223], v[16:19]
	v_mfma_f32_16x16x32_bf16 v[4:7], v[236:239], v[228:231], v[4:7]
	v_mfma_f32_16x16x32_bf16 v[0:3], v[244:247], v[228:231], v[0:3]
	s_setprio 0
	s_add_i32 s74, s74, 2
	s_add_u32 s8, s8, 0x100
	s_addc_u32 s9, s9, 0
	s_add_u32 s65, s65, 0x100
	s_addc_u32 s71, s71, 0
	s_cmp_gt_u32 s74, 29
	s_barrier
	s_cbranch_scc0 .LBB0_157
	s_cmp_gt_i32 s70, 15
	s_cselect_b64 s[74:75], -1, 0
	s_cmp_lt_i32 s70, 16
	s_cselect_b64 s[72:73], -1, 0
	s_cmp_gt_i32 s12, 9
	s_mov_b64 s[8:9], -1
	s_cbranch_scc0 .LBB0_338
	s_cmp_gt_u32 s12, 11
	s_cbranch_scc0 .LBB0_272
	s_cmp_gt_u32 s12, 19
	s_mov_b64 s[80:81], -1
	s_cbranch_scc0 .LBB0_173
	s_cmp_gt_u32 s12, 27
	s_cbranch_scc0 .LBB0_170
	s_lshl_b32 s2, s12, 8
	s_cmp_gt_u32 s12, 35
	s_mov_b64 s[8:9], -1
	s_mov_b64 s[78:79], -1
	s_cbranch_scc0 .LBB0_168
	s_cmp_gt_u32 s12, 43
	s_mov_b64 s[10:11], -1
	s_cbranch_scc0 .LBB0_165
	s_add_i32 s20, s2, 0xffffd400
	s_mov_b64 s[10:11], 0

.LBB0_941:
	s_mul_i32 s54, s81, 0xc0
	v_add_u32_e32 v102, s54, v179
	v_mov_b32_e32 v104, v180
	v_cmp_lt_i32_e32 vcc, s77, v102
	v_add_u32_e32 v100, 0xfffff000, v102
	s_and_saveexec_b64 s[8:9], vcc
	s_xor_b64 s[8:9], exec, s[8:9]
	v_mov_b32_e32 v101, v157
	v_lshlrev_b64 v[96:97], 13, v[100:101]
	v_mov_b32_e32 v103, v157
	v_lshl_add_u64 v[98:99], s[14:15], 0, v[96:97]
	v_lshlrev_b64 v[96:97], 13, v[102:103]
	s_andn2_saveexec_b64 s[8:9], s[8:9]
	v_ashrrev_i32_e32 v103, 31, v102
	v_lshlrev_b64 v[96:97], 13, v[102:103]
	v_lshl_add_u64 v[98:99], s[12:13], 0, v[96:97]
	s_or_b64 exec, exec, s[8:9]
	v_lshrrev_b32_e32 v100, 10, v100
	v_cndmask_b32_e32 v102, 8, v100, vcc
	v_mov_b64_e32 v[100:101], s[94:95]
	v_mad_u64_u32 v[100:101], s[8:9], v102, s73, v[100:101]
	v_lshl_add_u64 v[102:103], v[100:101], 0, v[156:157]
	v_add_co_u32_e32 v106, vcc, s74, v102
	v_lshl_add_u64 v[110:111], v[98:99], 0, v[156:157]
	s_nop 0
	v_addc_co_u32_e32 v107, vcc, 0, v103, vcc
	global_load_dwordx4 v[200:203], v[110:111], off
	v_lshl_add_u64 v[112:113], v[158:159], 0, v[96:97]
	global_load_dwordx4 v[204:207], v[106:107], off
	v_lshl_add_u64 v[114:115], v[102:103], 0, s[46:47]
	global_load_dwordx4 v[208:211], v[110:111], off offset:64
	global_load_dwordx4 v[212:215], v[114:115], off offset:64
	global_load_dwordx4 v[216:219], v[110:111], off offset:512
	global_load_dwordx4 v[220:223], v[114:115], off offset:512
	global_load_dwordx4 v[224:227], v[110:111], off offset:576
	global_load_dwordx4 v[228:231], v[114:115], off offset:576
	v_xor_b32_e32 v105, 16, v197
	s_waitcnt vmcnt(6)
	v_pk_fma_f32 v[90:91], v[90:91], v[206:207], v[202:203]
	v_pk_fma_f32 v[88:89], v[88:89], v[204:205], v[200:201]
	global_store_dwordx4 v[112:113], v[88:91], off
	v_mul_f32_e32 v107, v89, v89
	v_mul_f32_e32 v108, v91, v91
	v_fmac_f32_e32 v107, v88, v88
	v_fmac_f32_e32 v108, v90, v90
	v_add_f32_e32 v107, v107, v108
	v_and_b32_e32 v106, 64, v197
	v_add_u32_e32 v106, 64, v106
	v_cmp_lt_i32_e32 vcc, v105, v106
	s_waitcnt vmcnt(5)
	v_pk_fma_f32 v[94:95], v[94:95], v[214:215], v[210:211]
	v_pk_fma_f32 v[92:93], v[92:93], v[212:213], v[208:209]
	global_store_dwordx4 v[112:113], v[92:95], off offset:64
	v_mul_f32_e32 v108, v93, v93
	v_mul_f32_e32 v109, v95, v95
	v_fmac_f32_e32 v108, v92, v92
	v_fmac_f32_e32 v109, v94, v94
	v_add_f32_e32 v108, v108, v109
	v_add_f32_e32 v107, v107, v108
	v_cndmask_b32_e32 v105, v197, v105, vcc
	v_lshlrev_b32_e32 v105, 2, v105
	s_waitcnt vmcnt(4)
	v_pk_fma_f32 v[86:87], v[86:87], v[222:223], v[218:219]
	v_pk_fma_f32 v[84:85], v[84:85], v[220:221], v[216:217]
	global_store_dwordx4 v[112:113], v[84:87], off offset:512
	v_mul_f32_e32 v108, v85, v85
	v_mul_f32_e32 v109, v87, v87
	v_fmac_f32_e32 v108, v84, v84
	v_fmac_f32_e32 v109, v86, v86
	v_add_f32_e32 v108, v108, v109
	v_add_f32_e32 v107, v107, v108
	s_waitcnt vmcnt(3)
	v_pk_fma_f32 v[70:71], v[70:71], v[230:231], v[226:227]
	v_pk_fma_f32 v[68:69], v[68:69], v[228:229], v[224:225]
	v_mul_f32_e32 v97, v71, v71
	v_mul_f32_e32 v96, v69, v69
	v_fmac_f32_e32 v96, v68, v68
	v_fmac_f32_e32 v97, v70, v70
	v_add_f32_e32 v96, v96, v97
	v_add_f32_e32 v96, v107, v96
	ds_bpermute_b32 v97, v105, v96
	v_xor_b32_e32 v98, 32, v197
	v_cmp_lt_i32_e32 vcc, v98, v106
	global_store_dwordx4 v[112:113], v[68:71], off offset:576
	s_waitcnt lgkmcnt(0)
	v_add_f32_e32 v96, v96, v97
	v_cndmask_b32_e32 v98, v197, v98, vcc
	v_lshlrev_b32_e32 v106, 2, v98
	ds_bpermute_b32 v97, v106, v96
	s_and_saveexec_b64 s[8:9], s[6:7]
	s_cbranch_execz .LBB0_947
	s_waitcnt lgkmcnt(0)
	v_add_f32_e32 v96, v96, v97
	ds_write_b32 v188, v96

.LBB0_951:
	s_or_b64 exec, exec, s[8:9]
	v_lshrrev_b32_e32 v98, 10, v98
	v_cndmask_b32_e32 v102, 8, v98, vcc
	v_mov_b64_e32 v[98:99], s[94:95]
	v_mad_u64_u32 v[98:99], s[8:9], v102, s73, v[98:99]
	v_lshl_add_u64 v[102:103], v[98:99], 0, v[156:157]
	v_add_co_u32_e32 v108, vcc, 0x4000, v102
	v_lshl_add_u64 v[112:113], v[100:101], 0, v[156:157]
	s_nop 0
	v_addc_co_u32_e32 v109, vcc, 0, v103, vcc
	global_load_dwordx4 v[200:203], v[112:113], off
	s_waitcnt lgkmcnt(0)
	v_lshl_add_u64 v[114:115], v[158:159], 0, v[96:97]
	global_load_dwordx4 v[204:207], v[108:109], off
	v_lshl_add_u64 v[116:117], v[102:103], 0, s[46:47]
	global_load_dwordx4 v[208:211], v[112:113], off offset:64
	global_load_dwordx4 v[212:215], v[116:117], off offset:64
	global_load_dwordx4 v[216:219], v[112:113], off offset:512
	global_load_dwordx4 v[220:223], v[116:117], off offset:512
	global_load_dwordx4 v[224:227], v[112:113], off offset:576
	global_load_dwordx4 v[228:231], v[116:117], off offset:576
	s_waitcnt vmcnt(6)
	v_pk_fma_f32 v[78:79], v[78:79], v[206:207], v[202:203]
	v_pk_fma_f32 v[76:77], v[76:77], v[204:205], v[200:201]
	global_store_dwordx4 v[114:115], v[76:79], off
	v_mul_f32_e32 v107, v77, v77
	v_mul_f32_e32 v108, v79, v79
	v_fmac_f32_e32 v107, v76, v76
	v_fmac_f32_e32 v108, v78, v78
	v_add_f32_e32 v107, v107, v108
	s_waitcnt vmcnt(5)
	v_pk_fma_f32 v[82:83], v[82:83], v[214:215], v[210:211]
	v_pk_fma_f32 v[80:81], v[80:81], v[212:213], v[208:209]
	global_store_dwordx4 v[114:115], v[80:83], off offset:64
	v_mul_f32_e32 v108, v81, v81
	v_mul_f32_e32 v109, v83, v83
	v_fmac_f32_e32 v108, v80, v80
	v_fmac_f32_e32 v109, v82, v82
	v_add_f32_e32 v108, v108, v109
	v_add_f32_e32 v107, v107, v108
	s_waitcnt vmcnt(4)
	v_pk_fma_f32 v[74:75], v[74:75], v[222:223], v[218:219]
	v_pk_fma_f32 v[72:73], v[72:73], v[220:221], v[216:217]
	global_store_dwordx4 v[114:115], v[72:75], off offset:512
	v_mul_f32_e32 v108, v73, v73
	v_mul_f32_e32 v109, v75, v75
	v_fmac_f32_e32 v108, v72, v72
	v_fmac_f32_e32 v109, v74, v74
	v_add_f32_e32 v108, v108, v109
	v_add_f32_e32 v107, v107, v108
	s_waitcnt vmcnt(3)
	v_pk_fma_f32 v[54:55], v[54:55], v[230:231], v[226:227]
	v_pk_fma_f32 v[52:53], v[52:53], v[228:229], v[224:225]
	v_mul_f32_e32 v97, v55, v55
	v_mul_f32_e32 v96, v53, v53
	v_fmac_f32_e32 v96, v52, v52
	v_fmac_f32_e32 v97, v54, v54
	v_add_f32_e32 v96, v96, v97
	v_add_f32_e32 v96, v107, v96
	ds_bpermute_b32 v97, v105, v96
	global_store_dwordx4 v[114:115], v[52:55], off offset:576
	s_waitcnt lgkmcnt(0)
	v_add_f32_e32 v96, v96, v97
	ds_bpermute_b32 v97, v106, v96
	s_and_saveexec_b64 s[8:9], s[6:7]
	s_cbranch_execz .LBB0_953
	s_waitcnt lgkmcnt(0)
	v_add_f32_e32 v96, v96, v97
	ds_write_b32 v189, v96

.LBB0_957:
	s_or_b64 exec, exec, s[8:9]
	v_lshrrev_b32_e32 v98, 10, v98
	v_cndmask_b32_e32 v102, 8, v98, vcc
	v_mov_b64_e32 v[98:99], s[94:95]
	v_mad_u64_u32 v[98:99], s[8:9], v102, s73, v[98:99]
	v_lshl_add_u64 v[102:103], v[98:99], 0, v[156:157]
	v_add_co_u32_e32 v108, vcc, 0x4000, v102
	v_lshl_add_u64 v[112:113], v[100:101], 0, v[156:157]
	s_nop 0
	v_addc_co_u32_e32 v109, vcc, 0, v103, vcc
	global_load_dwordx4 v[200:203], v[112:113], off
	s_waitcnt lgkmcnt(0)
	v_lshl_add_u64 v[114:115], v[158:159], 0, v[96:97]
	global_load_dwordx4 v[204:207], v[108:109], off
	v_lshl_add_u64 v[116:117], v[102:103], 0, s[46:47]
	global_load_dwordx4 v[208:211], v[112:113], off offset:64
	global_load_dwordx4 v[212:215], v[116:117], off offset:64
	global_load_dwordx4 v[216:219], v[112:113], off offset:512
	global_load_dwordx4 v[220:223], v[116:117], off offset:512
	global_load_dwordx4 v[224:227], v[112:113], off offset:576
	global_load_dwordx4 v[228:231], v[116:117], off offset:576
	s_waitcnt vmcnt(6)
	v_pk_fma_f32 v[62:63], v[62:63], v[206:207], v[202:203]
	v_pk_fma_f32 v[60:61], v[60:61], v[204:205], v[200:201]
	global_store_dwordx4 v[114:115], v[60:63], off
	v_mul_f32_e32 v107, v61, v61
	v_mul_f32_e32 v108, v63, v63
	v_fmac_f32_e32 v107, v60, v60
	v_fmac_f32_e32 v108, v62, v62
	v_add_f32_e32 v107, v107, v108
	s_waitcnt vmcnt(5)
	v_pk_fma_f32 v[66:67], v[66:67], v[214:215], v[210:211]
	v_pk_fma_f32 v[64:65], v[64:65], v[212:213], v[208:209]
	global_store_dwordx4 v[114:115], v[64:67], off offset:64
	v_mul_f32_e32 v108, v65, v65
	v_mul_f32_e32 v109, v67, v67
	v_fmac_f32_e32 v108, v64, v64
	v_fmac_f32_e32 v109, v66, v66
	v_add_f32_e32 v108, v108, v109
	v_add_f32_e32 v107, v107, v108
	s_waitcnt vmcnt(4)
	v_pk_fma_f32 v[58:59], v[58:59], v[222:223], v[218:219]
	v_pk_fma_f32 v[56:57], v[56:57], v[220:221], v[216:217]
	global_store_dwordx4 v[114:115], v[56:59], off offset:512
	v_mul_f32_e32 v108, v57, v57
	v_mul_f32_e32 v109, v59, v59
	v_fmac_f32_e32 v108, v56, v56
	v_fmac_f32_e32 v109, v58, v58
	v_add_f32_e32 v108, v108, v109
	v_add_f32_e32 v107, v107, v108
	s_waitcnt vmcnt(3)
	v_pk_fma_f32 v[38:39], v[38:39], v[230:231], v[226:227]
	v_pk_fma_f32 v[36:37], v[36:37], v[228:229], v[224:225]
	v_mul_f32_e32 v97, v39, v39
	v_mul_f32_e32 v96, v37, v37
	v_fmac_f32_e32 v96, v36, v36
	v_fmac_f32_e32 v97, v38, v38
	v_add_f32_e32 v96, v96, v97
	v_add_f32_e32 v96, v107, v96
	ds_bpermute_b32 v97, v105, v96
	global_store_dwordx4 v[114:115], v[36:39], off offset:576
	s_waitcnt lgkmcnt(0)
	v_add_f32_e32 v96, v96, v97
	ds_bpermute_b32 v97, v106, v96
	s_and_saveexec_b64 s[8:9], s[6:7]
	s_cbranch_execz .LBB0_959
	s_waitcnt lgkmcnt(0)
	v_add_f32_e32 v96, v96, v97
	ds_write_b32 v190, v96

.LBB0_963:
	s_or_b64 exec, exec, s[8:9]
	v_lshrrev_b32_e32 v98, 10, v98
	v_cndmask_b32_e32 v102, 8, v98, vcc
	v_mov_b64_e32 v[98:99], s[94:95]
	v_mad_u64_u32 v[98:99], s[8:9], v102, s73, v[98:99]
	v_lshl_add_u64 v[102:103], v[98:99], 0, v[156:157]
	v_add_co_u32_e32 v108, vcc, 0x4000, v102
	v_lshl_add_u64 v[112:113], v[100:101], 0, v[156:157]
	s_nop 0
	v_addc_co_u32_e32 v109, vcc, 0, v103, vcc
	global_load_dwordx4 v[200:203], v[112:113], off
	s_waitcnt lgkmcnt(0)
	v_lshl_add_u64 v[114:115], v[158:159], 0, v[96:97]
	global_load_dwordx4 v[204:207], v[108:109], off
	v_lshl_add_u64 v[116:117], v[102:103], 0, s[46:47]
	global_load_dwordx4 v[208:211], v[112:113], off offset:64
	global_load_dwordx4 v[212:215], v[116:117], off offset:64
	global_load_dwordx4 v[216:219], v[112:113], off offset:512
	global_load_dwordx4 v[220:223], v[116:117], off offset:512
	global_load_dwordx4 v[224:227], v[112:113], off offset:576
	global_load_dwordx4 v[228:231], v[116:117], off offset:576
	s_waitcnt vmcnt(6)
	v_pk_fma_f32 v[46:47], v[46:47], v[206:207], v[202:203]
	v_pk_fma_f32 v[44:45], v[44:45], v[204:205], v[200:201]
	global_store_dwordx4 v[114:115], v[44:47], off
	v_mul_f32_e32 v107, v45, v45
	v_mul_f32_e32 v108, v47, v47
	v_fmac_f32_e32 v107, v44, v44
	v_fmac_f32_e32 v108, v46, v46
	v_add_f32_e32 v107, v107, v108
	s_waitcnt vmcnt(5)
	v_pk_fma_f32 v[50:51], v[50:51], v[214:215], v[210:211]
	v_pk_fma_f32 v[48:49], v[48:49], v[212:213], v[208:209]
	global_store_dwordx4 v[114:115], v[48:51], off offset:64
	v_mul_f32_e32 v108, v49, v49
	v_mul_f32_e32 v109, v51, v51
	v_fmac_f32_e32 v108, v48, v48
	v_fmac_f32_e32 v109, v50, v50
	v_add_f32_e32 v108, v108, v109
	v_add_f32_e32 v107, v107, v108
	s_waitcnt vmcnt(4)
	v_pk_fma_f32 v[42:43], v[42:43], v[222:223], v[218:219]
	v_pk_fma_f32 v[40:41], v[40:41], v[220:221], v[216:217]
	global_store_dwordx4 v[114:115], v[40:43], off offset:512
	v_mul_f32_e32 v108, v41, v41
	v_mul_f32_e32 v109, v43, v43
	v_fmac_f32_e32 v108, v40, v40
	v_fmac_f32_e32 v109, v42, v42
	v_add_f32_e32 v108, v108, v109
	v_add_f32_e32 v107, v107, v108
	s_waitcnt vmcnt(3)
	v_pk_fma_f32 v[22:23], v[22:23], v[230:231], v[226:227]
	v_pk_fma_f32 v[20:21], v[20:21], v[228:229], v[224:225]
	v_mul_f32_e32 v97, v23, v23
	v_mul_f32_e32 v96, v21, v21
	v_fmac_f32_e32 v96, v20, v20
	v_fmac_f32_e32 v97, v22, v22
	v_add_f32_e32 v96, v96, v97
	v_add_f32_e32 v96, v107, v96
	ds_bpermute_b32 v97, v105, v96
	global_store_dwordx4 v[114:115], v[20:23], off offset:576
	s_waitcnt lgkmcnt(0)
	v_add_f32_e32 v96, v96, v97
	ds_bpermute_b32 v97, v106, v96
	s_and_saveexec_b64 s[8:9], s[6:7]
	s_cbranch_execz .LBB0_965
	s_waitcnt lgkmcnt(0)
	v_add_f32_e32 v96, v96, v97
	ds_write_b32 v191, v96

.LBB0_969:
	s_or_b64 exec, exec, s[8:9]
	v_lshrrev_b32_e32 v98, 10, v98
	v_cndmask_b32_e32 v102, 8, v98, vcc
	v_mov_b64_e32 v[98:99], s[94:95]
	v_mad_u64_u32 v[98:99], s[8:9], v102, s73, v[98:99]
	v_lshl_add_u64 v[102:103], v[98:99], 0, v[156:157]
	v_add_co_u32_e32 v108, vcc, 0x4000, v102
	v_lshl_add_u64 v[112:113], v[100:101], 0, v[156:157]
	s_nop 0
	v_addc_co_u32_e32 v109, vcc, 0, v103, vcc
	global_load_dwordx4 v[200:203], v[112:113], off
	s_waitcnt lgkmcnt(0)
	v_lshl_add_u64 v[114:115], v[158:159], 0, v[96:97]
	global_load_dwordx4 v[204:207], v[108:109], off
	v_lshl_add_u64 v[116:117], v[102:103], 0, s[46:47]
	global_load_dwordx4 v[208:211], v[112:113], off offset:64
	global_load_dwordx4 v[212:215], v[116:117], off offset:64
	global_load_dwordx4 v[216:219], v[112:113], off offset:512
	global_load_dwordx4 v[220:223], v[116:117], off offset:512
	global_load_dwordx4 v[224:227], v[112:113], off offset:576
	global_load_dwordx4 v[228:231], v[116:117], off offset:576
	s_waitcnt vmcnt(6)
	v_pk_fma_f32 v[30:31], v[30:31], v[206:207], v[202:203]
	v_pk_fma_f32 v[28:29], v[28:29], v[204:205], v[200:201]
	global_store_dwordx4 v[114:115], v[28:31], off
	v_mul_f32_e32 v107, v29, v29
	v_mul_f32_e32 v108, v31, v31
	v_fmac_f32_e32 v107, v28, v28
	v_fmac_f32_e32 v108, v30, v30
	v_add_f32_e32 v107, v107, v108
	s_waitcnt vmcnt(5)
	v_pk_fma_f32 v[34:35], v[34:35], v[214:215], v[210:211]
	v_pk_fma_f32 v[32:33], v[32:33], v[212:213], v[208:209]
	global_store_dwordx4 v[114:115], v[32:35], off offset:64
	v_mul_f32_e32 v108, v33, v33
	v_mul_f32_e32 v109, v35, v35
	v_fmac_f32_e32 v108, v32, v32
	v_fmac_f32_e32 v109, v34, v34
	v_add_f32_e32 v108, v108, v109
	v_add_f32_e32 v107, v107, v108
	s_waitcnt vmcnt(4)
	v_pk_fma_f32 v[26:27], v[26:27], v[222:223], v[218:219]
	v_pk_fma_f32 v[24:25], v[24:25], v[220:221], v[216:217]
	global_store_dwordx4 v[114:115], v[24:27], off offset:512
	v_mul_f32_e32 v108, v25, v25
	v_mul_f32_e32 v109, v27, v27
	v_fmac_f32_e32 v108, v24, v24
	v_fmac_f32_e32 v109, v26, v26
	v_add_f32_e32 v108, v108, v109
	v_add_f32_e32 v107, v107, v108
	s_waitcnt vmcnt(3)
	v_pk_fma_f32 v[18:19], v[18:19], v[230:231], v[226:227]
	v_pk_fma_f32 v[16:17], v[16:17], v[228:229], v[224:225]
	v_mul_f32_e32 v97, v19, v19
	v_mul_f32_e32 v96, v17, v17
	v_fmac_f32_e32 v96, v16, v16
	v_fmac_f32_e32 v97, v18, v18
	v_add_f32_e32 v96, v96, v97
	v_add_f32_e32 v96, v107, v96
	ds_bpermute_b32 v97, v105, v96
	global_store_dwordx4 v[114:115], v[16:19], off offset:576
	s_waitcnt lgkmcnt(0)
	v_add_f32_e32 v96, v96, v97
	ds_bpermute_b32 v97, v106, v96
	s_and_saveexec_b64 s[8:9], s[6:7]
	s_cbranch_execz .LBB0_971
	s_waitcnt lgkmcnt(0)
	v_add_f32_e32 v96, v96, v97
	ds_write_b32 v192, v96

.LBB0_975:
	s_or_b64 exec, exec, s[8:9]
	v_lshrrev_b32_e32 v98, 10, v98
	v_cndmask_b32_e32 v102, 8, v98, vcc
	v_mov_b64_e32 v[98:99], s[94:95]
	v_mad_u64_u32 v[98:99], s[8:9], v102, s73, v[98:99]
	v_lshl_add_u64 v[102:103], v[98:99], 0, v[156:157]
	v_add_co_u32_e32 v108, vcc, 0x4000, v102
	v_lshl_add_u64 v[112:113], v[100:101], 0, v[156:157]
	s_nop 0
	v_addc_co_u32_e32 v109, vcc, 0, v103, vcc
	global_load_dwordx4 v[200:203], v[112:113], off
	s_waitcnt lgkmcnt(0)
	v_lshl_add_u64 v[114:115], v[158:159], 0, v[96:97]
	global_load_dwordx4 v[204:207], v[108:109], off
	v_lshl_add_u64 v[116:117], v[102:103], 0, s[46:47]
	global_load_dwordx4 v[208:211], v[112:113], off offset:64
	global_load_dwordx4 v[212:215], v[116:117], off offset:64
	global_load_dwordx4 v[216:219], v[112:113], off offset:512
	global_load_dwordx4 v[220:223], v[116:117], off offset:512
	global_load_dwordx4 v[224:227], v[112:113], off offset:576
	global_load_dwordx4 v[228:231], v[116:117], off offset:576
	s_waitcnt vmcnt(6)
	v_pk_fma_f32 v[14:15], v[14:15], v[206:207], v[202:203]
	v_pk_fma_f32 v[12:13], v[12:13], v[204:205], v[200:201]
	global_store_dwordx4 v[114:115], v[12:15], off
	v_mul_f32_e32 v107, v13, v13
	v_mul_f32_e32 v108, v15, v15
	v_fmac_f32_e32 v107, v12, v12
	v_fmac_f32_e32 v108, v14, v14
	v_add_f32_e32 v107, v107, v108
	s_waitcnt vmcnt(5)
	v_pk_fma_f32 v[10:11], v[10:11], v[214:215], v[210:211]
	v_pk_fma_f32 v[8:9], v[8:9], v[212:213], v[208:209]
	global_store_dwordx4 v[114:115], v[8:11], off offset:64
	v_mul_f32_e32 v108, v9, v9
	v_mul_f32_e32 v109, v11, v11
	v_fmac_f32_e32 v108, v8, v8
	v_fmac_f32_e32 v109, v10, v10
	v_add_f32_e32 v108, v108, v109
	v_add_f32_e32 v107, v107, v108
	s_waitcnt vmcnt(4)
	v_pk_fma_f32 v[6:7], v[6:7], v[222:223], v[218:219]
	v_pk_fma_f32 v[4:5], v[4:5], v[220:221], v[216:217]
	global_store_dwordx4 v[114:115], v[4:7], off offset:512
	v_mul_f32_e32 v108, v5, v5
	v_mul_f32_e32 v109, v7, v7
	v_fmac_f32_e32 v108, v4, v4
	v_fmac_f32_e32 v109, v6, v6
	v_add_f32_e32 v108, v108, v109
	v_add_f32_e32 v107, v107, v108
	s_waitcnt vmcnt(3)
	v_pk_fma_f32 v[2:3], v[2:3], v[230:231], v[226:227]
	v_pk_fma_f32 v[0:1], v[0:1], v[228:229], v[224:225]
	v_mul_f32_e32 v97, v3, v3
	v_mul_f32_e32 v96, v1, v1
	v_fmac_f32_e32 v96, v0, v0
	v_fmac_f32_e32 v97, v2, v2
	v_add_f32_e32 v96, v96, v97
	v_add_f32_e32 v96, v107, v96
	ds_bpermute_b32 v97, v105, v96
	global_store_dwordx4 v[114:115], v[0:3], off offset:576
	s_waitcnt lgkmcnt(0)
	v_add_f32_e32 v96, v96, v97
	ds_bpermute_b32 v97, v106, v96
	s_and_saveexec_b64 s[8:9], s[6:7]
	s_cbranch_execz .LBB0_977
	s_waitcnt lgkmcnt(0)
	v_add_f32_e32 v96, v96, v97
	ds_write_b32 v193, v96

.LBB0_1064:
	s_ashr_i32 s15, s14, 31
	s_lshl_b64 s[20:21], s[14:15], 20
	s_add_u32 s20, s3, s20
	s_addc_u32 s21, s33, s21
	s_and_b64 s[22:23], s[30:31], exec
	s_cselect_b32 s15, s21, s27
	s_cselect_b32 s25, s20, s26
	s_ashr_i32 s17, s16, 31
	s_lshl_b64 s[22:23], s[16:17], 20
	s_add_u32 s22, s38, s22
	s_addc_u32 s23, s39, s23
	s_and_b64 s[30:31], s[30:31], exec
	s_cselect_b32 s17, s23, s29
	s_cselect_b32 s56, s22, s28
	s_add_u32 s26, s26, 0x80080
	s_addc_u32 s27, s27, 0
	s_add_u32 s57, s28, 0x100
	v_mov_b32_e32 v0, 0
	s_addc_u32 s58, s29, 0
	s_mov_b32 s59, -2
	v_mov_b32_e32 v1, v0
	v_mov_b32_e32 v2, v0
	v_mov_b32_e32 v3, v0
	v_mov_b32_e32 v4, v0
	v_mov_b32_e32 v5, v0
	v_mov_b32_e32 v6, v0
	v_mov_b32_e32 v7, v0
	v_mov_b32_e32 v16, v0
	v_mov_b32_e32 v17, v0
	v_mov_b32_e32 v18, v0
	v_mov_b32_e32 v19, v0
	v_mov_b32_e32 v20, v0
	v_mov_b32_e32 v21, v0
	v_mov_b32_e32 v22, v0
	v_mov_b32_e32 v23, v0
	v_mov_b32_e32 v32, v0
	v_mov_b32_e32 v33, v0
	v_mov_b32_e32 v34, v0
	v_mov_b32_e32 v35, v0
	v_mov_b32_e32 v36, v0
	v_mov_b32_e32 v37, v0
	v_mov_b32_e32 v38, v0
	v_mov_b32_e32 v39, v0
	v_mov_b32_e32 v48, v0
	v_mov_b32_e32 v49, v0
	v_mov_b32_e32 v50, v0
	v_mov_b32_e32 v51, v0
	v_mov_b32_e32 v52, v0
	v_mov_b32_e32 v53, v0
	v_mov_b32_e32 v54, v0
	v_mov_b32_e32 v55, v0
	v_mov_b32_e32 v8, v0
	v_mov_b32_e32 v9, v0
	v_mov_b32_e32 v10, v0
	v_mov_b32_e32 v11, v0
	v_mov_b32_e32 v12, v0
	v_mov_b32_e32 v13, v0
	v_mov_b32_e32 v14, v0
	v_mov_b32_e32 v15, v0
	v_mov_b32_e32 v24, v0
	v_mov_b32_e32 v25, v0
	v_mov_b32_e32 v26, v0
	v_mov_b32_e32 v27, v0
	v_mov_b32_e32 v28, v0
	v_mov_b32_e32 v29, v0
	v_mov_b32_e32 v30, v0
	v_mov_b32_e32 v31, v0
	v_mov_b32_e32 v40, v0
	v_mov_b32_e32 v41, v0
	v_mov_b32_e32 v42, v0
	v_mov_b32_e32 v43, v0
	v_mov_b32_e32 v44, v0
	v_mov_b32_e32 v45, v0
	v_mov_b32_e32 v46, v0
	v_mov_b32_e32 v47, v0
	v_mov_b32_e32 v56, v0
	v_mov_b32_e32 v57, v0
	v_mov_b32_e32 v58, v0
	v_mov_b32_e32 v59, v0
	v_mov_b32_e32 v60, v0
	v_mov_b32_e32 v61, v0
	v_mov_b32_e32 v62, v0
	v_mov_b32_e32 v63, v0
	v_mov_b32_e32 v64, v0
	v_mov_b32_e32 v65, v0
	v_mov_b32_e32 v66, v0
	v_mov_b32_e32 v67, v0
	v_mov_b32_e32 v68, v0
	v_mov_b32_e32 v69, v0
	v_mov_b32_e32 v70, v0
	v_mov_b32_e32 v71, v0
	v_mov_b32_e32 v80, v0
	v_mov_b32_e32 v81, v0
	v_mov_b32_e32 v82, v0
	v_mov_b32_e32 v83, v0
	v_mov_b32_e32 v84, v0
	v_mov_b32_e32 v85, v0
	v_mov_b32_e32 v86, v0
	v_mov_b32_e32 v87, v0
	v_mov_b32_e32 v96, v0
	v_mov_b32_e32 v97, v0
	v_mov_b32_e32 v98, v0
	v_mov_b32_e32 v99, v0
	v_mov_b32_e32 v100, v0
	v_mov_b32_e32 v101, v0
	v_mov_b32_e32 v102, v0
	v_mov_b32_e32 v103, v0
	v_mov_b32_e32 v112, v0
	v_mov_b32_e32 v113, v0
	v_mov_b32_e32 v114, v0
	v_mov_b32_e32 v115, v0
	v_mov_b32_e32 v116, v0
	v_mov_b32_e32 v117, v0
	v_mov_b32_e32 v118, v0
	v_mov_b32_e32 v119, v0
	v_mov_b32_e32 v72, v0
	v_mov_b32_e32 v73, v0
	v_mov_b32_e32 v74, v0
	v_mov_b32_e32 v75, v0
	v_mov_b32_e32 v76, v0
	v_mov_b32_e32 v77, v0
	v_mov_b32_e32 v78, v0
	v_mov_b32_e32 v79, v0
	v_mov_b32_e32 v88, v0
	v_mov_b32_e32 v89, v0
	v_mov_b32_e32 v90, v0
	v_mov_b32_e32 v91, v0
	v_mov_b32_e32 v92, v0
	v_mov_b32_e32 v93, v0
	v_mov_b32_e32 v94, v0
	v_mov_b32_e32 v95, v0
	v_mov_b32_e32 v104, v0
	v_mov_b32_e32 v105, v0
	v_mov_b32_e32 v106, v0
	v_mov_b32_e32 v107, v0
	v_mov_b32_e32 v108, v0
	v_mov_b32_e32 v109, v0
	v_mov_b32_e32 v110, v0
	v_mov_b32_e32 v111, v0
	v_mov_b32_e32 v120, v0
	v_mov_b32_e32 v121, v0
	v_mov_b32_e32 v122, v0
	v_mov_b32_e32 v123, v0
	v_mov_b32_e32 v124, v0
	v_mov_b32_e32 v125, v0
	v_mov_b32_e32 v126, v0
	v_mov_b32_e32 v127, v0
	.p2align 6
.LBB0_1065:
	ds_read_b128 v[152:155], v148
	ds_read_b128 v[156:159], v148 offset:1024
	ds_read_b128 v[160:163], v148 offset:2048
	ds_read_b128 v[164:167], v148 offset:3072
	s_add_u32 s28, s26, 0xfff80080
	s_addc_u32 s29, s27, -1
	s_cmp_eq_u32 s59, 28
	s_cselect_b32 s31, s15, s29
	s_cselect_b32 s30, s25, s28
	s_cselect_b32 s29, s17, s58
	s_cselect_b32 s28, s56, s57
	s_add_i32 m0, s47, 0xc000
	ds_read_b128 v[168:171], v149
	ds_read_b128 v[172:175], v149 offset:1024
	ds_read_b128 v[176:179], v149 offset:2048
	ds_read_b128 v[180:183], v149 offset:3072
	global_load_lds_dwordx4 v138, s[26:27]
	s_add_i32 m0, s47, 0xe000
	ds_read_b128 v[186:189], v149 offset:4096
	ds_read_b128 v[190:193], v149 offset:5120
	ds_read_b128 v[194:197], v149 offset:6144
	ds_read_b128 v[198:201], v149 offset:7168
	global_load_lds_dwordx4 v140, s[26:27]
	s_waitcnt lgkmcnt(8)
	s_barrier
	s_waitcnt lgkmcnt(0)
	s_setprio 1
	v_mfma_f32_16x16x32_bf16 v[124:127], v[152:155], v[168:171], v[124:127]
	v_mfma_f32_16x16x32_bf16 v[120:123], v[160:163], v[168:171], v[120:123]
	v_mfma_f32_16x16x32_bf16 v[108:111], v[152:155], v[176:179], v[108:111]
	v_mfma_f32_16x16x32_bf16 v[104:107], v[160:163], v[176:179], v[104:107]
	v_mfma_f32_16x16x32_bf16 v[92:95], v[152:155], v[186:189], v[92:95]
	v_mfma_f32_16x16x32_bf16 v[88:91], v[160:163], v[186:189], v[88:91]
	v_mfma_f32_16x16x32_bf16 v[76:79], v[152:155], v[194:197], v[76:79]
	v_mfma_f32_16x16x32_bf16 v[72:75], v[160:163], v[194:197], v[72:75]
	v_mfma_f32_16x16x32_bf16 v[124:127], v[156:159], v[172:175], v[124:127]
	v_mfma_f32_16x16x32_bf16 v[120:123], v[164:167], v[172:175], v[120:123]
	v_mfma_f32_16x16x32_bf16 v[108:111], v[156:159], v[180:183], v[108:111]
	v_mfma_f32_16x16x32_bf16 v[104:107], v[164:167], v[180:183], v[104:107]
	v_mfma_f32_16x16x32_bf16 v[92:95], v[156:159], v[190:193], v[92:95]
	v_mfma_f32_16x16x32_bf16 v[88:91], v[164:167], v[190:193], v[88:91]
	v_mfma_f32_16x16x32_bf16 v[76:79], v[156:159], v[198:201], v[76:79]
	v_mfma_f32_16x16x32_bf16 v[72:75], v[164:167], v[198:201], v[72:75]
	s_setprio 0
	s_barrier
	s_add_i32 m0, s47, 0x10000
	ds_read_b128 v[202:205], v150
	ds_read_b128 v[206:209], v150 offset:1024
	global_load_lds_dwordx4 v132, s[28:29]
	s_add_i32 m0, s47, 0x12000
	ds_read_b128 v[210:213], v150 offset:2048
	ds_read_b128 v[214:217], v150 offset:3072
	global_load_lds_dwordx4 v128, s[28:29]
	s_barrier
	s_waitcnt lgkmcnt(0)
	s_setprio 1
	v_mfma_f32_16x16x32_bf16 v[116:119], v[202:205], v[168:171], v[116:119]
	v_mfma_f32_16x16x32_bf16 v[112:115], v[210:213], v[168:171], v[112:115]
	v_mfma_f32_16x16x32_bf16 v[100:103], v[202:205], v[176:179], v[100:103]
	v_mfma_f32_16x16x32_bf16 v[96:99], v[210:213], v[176:179], v[96:99]
	v_mfma_f32_16x16x32_bf16 v[84:87], v[202:205], v[186:189], v[84:87]
	v_mfma_f32_16x16x32_bf16 v[80:83], v[210:213], v[186:189], v[80:83]
	v_mfma_f32_16x16x32_bf16 v[68:71], v[202:205], v[194:197], v[68:71]
	v_mfma_f32_16x16x32_bf16 v[64:67], v[210:213], v[194:197], v[64:67]
	v_mfma_f32_16x16x32_bf16 v[116:119], v[206:209], v[172:175], v[116:119]
	v_mfma_f32_16x16x32_bf16 v[112:115], v[214:217], v[172:175], v[112:115]
	v_mfma_f32_16x16x32_bf16 v[100:103], v[206:209], v[180:183], v[100:103]
	v_mfma_f32_16x16x32_bf16 v[96:99], v[214:217], v[180:183], v[96:99]
	v_mfma_f32_16x16x32_bf16 v[84:87], v[206:209], v[190:193], v[84:87]
	v_mfma_f32_16x16x32_bf16 v[80:83], v[214:217], v[190:193], v[80:83]
	v_mfma_f32_16x16x32_bf16 v[68:71], v[206:209], v[198:201], v[68:71]
	v_mfma_f32_16x16x32_bf16 v[64:67], v[214:217], v[198:201], v[64:67]
	s_setprio 0
	s_barrier
	s_mov_b32 m0, s47
	ds_read_b128 v[168:171], v149 offset:16384
	ds_read_b128 v[172:175], v149 offset:17408
	ds_read_b128 v[176:179], v149 offset:18432
	ds_read_b128 v[180:183], v149 offset:19456
	global_load_lds_dwordx4 v134, s[30:31]
	s_mov_b32 m0, s48
	ds_read_b128 v[186:189], v149 offset:20480
	ds_read_b128 v[190:193], v149 offset:21504
	ds_read_b128 v[194:197], v149 offset:22528
	ds_read_b128 v[198:201], v149 offset:23552
	global_load_lds_dwordx4 v130, s[30:31]
	s_barrier
	s_waitcnt lgkmcnt(0)
	s_setprio 1
	v_mfma_f32_16x16x32_bf16 v[60:63], v[152:155], v[168:171], v[60:63]
	v_mfma_f32_16x16x32_bf16 v[56:59], v[160:163], v[168:171], v[56:59]
	v_mfma_f32_16x16x32_bf16 v[44:47], v[152:155], v[176:179], v[44:47]
	v_mfma_f32_16x16x32_bf16 v[40:43], v[160:163], v[176:179], v[40:43]
	v_mfma_f32_16x16x32_bf16 v[28:31], v[152:155], v[186:189], v[28:31]
	v_mfma_f32_16x16x32_bf16 v[24:27], v[160:163], v[186:189], v[24:27]
	v_mfma_f32_16x16x32_bf16 v[12:15], v[152:155], v[194:197], v[12:15]
	v_mfma_f32_16x16x32_bf16 v[8:11], v[160:163], v[194:197], v[8:11]
	v_mfma_f32_16x16x32_bf16 v[60:63], v[156:159], v[172:175], v[60:63]
	v_mfma_f32_16x16x32_bf16 v[56:59], v[164:167], v[172:175], v[56:59]
	v_mfma_f32_16x16x32_bf16 v[44:47], v[156:159], v[180:183], v[44:47]
	v_mfma_f32_16x16x32_bf16 v[40:43], v[164:167], v[180:183], v[40:43]
	v_mfma_f32_16x16x32_bf16 v[28:31], v[156:159], v[190:193], v[28:31]
	v_mfma_f32_16x16x32_bf16 v[24:27], v[164:167], v[190:193], v[24:27]
	v_mfma_f32_16x16x32_bf16 v[12:15], v[156:159], v[198:201], v[12:15]
	v_mfma_f32_16x16x32_bf16 v[8:11], v[164:167], v[198:201], v[8:11]
	s_setprio 0
	s_barrier
	s_add_u32 s34, s28, 0x80000
	s_addc_u32 s35, s29, 0
	s_add_i32 m0, s47, 0x14000
	s_nop 0
	global_load_lds_dwordx4 v132, s[34:35]
	s_add_i32 m0, s47, 0x16000
	s_nop 0
	global_load_lds_dwordx4 v128, s[34:35]
	s_waitcnt vmcnt(6)
	s_barrier
	s_setprio 1
	v_mfma_f32_16x16x32_bf16 v[52:55], v[202:205], v[168:171], v[52:55]
	v_mfma_f32_16x16x32_bf16 v[48:51], v[210:213], v[168:171], v[48:51]
	v_mfma_f32_16x16x32_bf16 v[36:39], v[202:205], v[176:179], v[36:39]
	v_mfma_f32_16x16x32_bf16 v[32:35], v[210:213], v[176:179], v[32:35]
	v_mfma_f32_16x16x32_bf16 v[20:23], v[202:205], v[186:189], v[20:23]
	v_mfma_f32_16x16x32_bf16 v[16:19], v[210:213], v[186:189], v[16:19]
	v_mfma_f32_16x16x32_bf16 v[4:7], v[202:205], v[194:197], v[4:7]
	v_mfma_f32_16x16x32_bf16 v[0:3], v[210:213], v[194:197], v[0:3]
	v_mfma_f32_16x16x32_bf16 v[52:55], v[206:209], v[172:175], v[52:55]
	v_mfma_f32_16x16x32_bf16 v[48:51], v[214:217], v[172:175], v[48:51]
	v_mfma_f32_16x16x32_bf16 v[36:39], v[206:209], v[180:183], v[36:39]
	v_mfma_f32_16x16x32_bf16 v[32:35], v[214:217], v[180:183], v[32:35]
	v_mfma_f32_16x16x32_bf16 v[20:23], v[206:209], v[190:193], v[20:23]
	v_mfma_f32_16x16x32_bf16 v[16:19], v[214:217], v[190:193], v[16:19]
	v_mfma_f32_16x16x32_bf16 v[4:7], v[206:209], v[198:201], v[4:7]
	v_mfma_f32_16x16x32_bf16 v[0:3], v[214:217], v[198:201], v[0:3]
	s_setprio 0
	s_barrier
	s_add_i32 s34, 0, 0x18000
	v_add_u32_e32 v151, s34, v147
	ds_read_b128 v[152:155], v151
	ds_read_b128 v[156:159], v151 offset:1024
	ds_read_b128 v[160:163], v151 offset:2048
	ds_read_b128 v[164:167], v151 offset:3072
	s_add_u32 s34, s30, 0x80000
	s_addc_u32 s35, s31, 0
	s_mov_b32 m0, s49
	ds_read_b128 v[168:171], v149 offset:32768
	ds_read_b128 v[172:175], v149 offset:33792
	ds_read_b128 v[176:179], v149 offset:34816
	ds_read_b128 v[180:183], v149 offset:35840
	global_load_lds_dwordx4 v134, s[34:35]
	s_mov_b32 m0, s50
	ds_read_b128 v[186:189], v149 offset:36864
	ds_read_b128 v[190:193], v149 offset:37888
	ds_read_b128 v[194:197], v149 offset:38912
	ds_read_b128 v[198:201], v149 offset:39936
	global_load_lds_dwordx4 v130, s[34:35]
	s_waitcnt lgkmcnt(8)
	s_barrier
	s_waitcnt lgkmcnt(0)
	s_setprio 1
	v_mfma_f32_16x16x32_bf16 v[124:127], v[152:155], v[168:171], v[124:127]
	v_mfma_f32_16x16x32_bf16 v[120:123], v[160:163], v[168:171], v[120:123]
	v_mfma_f32_16x16x32_bf16 v[108:111], v[152:155], v[176:179], v[108:111]
	v_mfma_f32_16x16x32_bf16 v[104:107], v[160:163], v[176:179], v[104:107]
	v_mfma_f32_16x16x32_bf16 v[92:95], v[152:155], v[186:189], v[92:95]
	v_mfma_f32_16x16x32_bf16 v[88:91], v[160:163], v[186:189], v[88:91]
	v_mfma_f32_16x16x32_bf16 v[76:79], v[152:155], v[194:197], v[76:79]
	v_mfma_f32_16x16x32_bf16 v[72:75], v[160:163], v[194:197], v[72:75]
	v_mfma_f32_16x16x32_bf16 v[124:127], v[156:159], v[172:175], v[124:127]
	v_mfma_f32_16x16x32_bf16 v[120:123], v[164:167], v[172:175], v[120:123]
	v_mfma_f32_16x16x32_bf16 v[108:111], v[156:159], v[180:183], v[108:111]
	v_mfma_f32_16x16x32_bf16 v[104:107], v[164:167], v[180:183], v[104:107]
	v_mfma_f32_16x16x32_bf16 v[92:95], v[156:159], v[190:193], v[92:95]
	v_mfma_f32_16x16x32_bf16 v[88:91], v[164:167], v[190:193], v[88:91]
	v_mfma_f32_16x16x32_bf16 v[76:79], v[156:159], v[198:201], v[76:79]
	v_mfma_f32_16x16x32_bf16 v[72:75], v[164:167], v[198:201], v[72:75]
	s_setprio 0
	s_barrier
	s_add_i32 s34, 0, 0x1c000
	v_add_u32_e32 v151, s34, v147
	s_add_u32 s34, s28, 0x80
	s_addc_u32 s35, s29, 0
	s_add_i32 m0, s47, 0x18000
	ds_read_b128 v[202:205], v151
	ds_read_b128 v[206:209], v151 offset:1024
	global_load_lds_dwordx4 v132, s[34:35]
	s_add_i32 m0, s47, 0x1a000
	ds_read_b128 v[210:213], v151 offset:2048
	ds_read_b128 v[214:217], v151 offset:3072
	global_load_lds_dwordx4 v128, s[34:35]
	s_barrier
	s_waitcnt lgkmcnt(0)
	s_setprio 1
	v_mfma_f32_16x16x32_bf16 v[116:119], v[202:205], v[168:171], v[116:119]
	v_mfma_f32_16x16x32_bf16 v[112:115], v[210:213], v[168:171], v[112:115]
	v_mfma_f32_16x16x32_bf16 v[100:103], v[202:205], v[176:179], v[100:103]
	v_mfma_f32_16x16x32_bf16 v[96:99], v[210:213], v[176:179], v[96:99]
	v_mfma_f32_16x16x32_bf16 v[84:87], v[202:205], v[186:189], v[84:87]
	v_mfma_f32_16x16x32_bf16 v[80:83], v[210:213], v[186:189], v[80:83]
	v_mfma_f32_16x16x32_bf16 v[68:71], v[202:205], v[194:197], v[68:71]
	v_mfma_f32_16x16x32_bf16 v[64:67], v[210:213], v[194:197], v[64:67]
	v_mfma_f32_16x16x32_bf16 v[116:119], v[206:209], v[172:175], v[116:119]
	v_mfma_f32_16x16x32_bf16 v[112:115], v[214:217], v[172:175], v[112:115]
	v_mfma_f32_16x16x32_bf16 v[100:103], v[206:209], v[180:183], v[100:103]
	v_mfma_f32_16x16x32_bf16 v[96:99], v[214:217], v[180:183], v[96:99]
	v_mfma_f32_16x16x32_bf16 v[84:87], v[206:209], v[190:193], v[84:87]
	v_mfma_f32_16x16x32_bf16 v[80:83], v[214:217], v[190:193], v[80:83]
	v_mfma_f32_16x16x32_bf16 v[68:71], v[206:209], v[198:201], v[68:71]
	v_mfma_f32_16x16x32_bf16 v[64:67], v[214:217], v[198:201], v[64:67]
	s_setprio 0
	s_barrier
	s_add_u32 s34, s30, 0x80
	s_addc_u32 s35, s31, 0
	s_mov_b32 m0, s51
	ds_read_b128 v[168:171], v149 offset:49152
	ds_read_b128 v[172:175], v149 offset:50176
	ds_read_b128 v[176:179], v149 offset:51200
	ds_read_b128 v[180:183], v149 offset:52224
	global_load_lds_dwordx4 v134, s[34:35]
	s_mov_b32 m0, s52
	ds_read_b128 v[186:189], v149 offset:53248
	ds_read_b128 v[190:193], v149 offset:54272
	ds_read_b128 v[194:197], v149 offset:55296
	ds_read_b128 v[198:201], v149 offset:56320
	global_load_lds_dwordx4 v130, s[34:35]
	s_barrier
	s_waitcnt lgkmcnt(0)
	s_setprio 1
	v_mfma_f32_16x16x32_bf16 v[60:63], v[152:155], v[168:171], v[60:63]
	v_mfma_f32_16x16x32_bf16 v[56:59], v[160:163], v[168:171], v[56:59]
	v_mfma_f32_16x16x32_bf16 v[44:47], v[152:155], v[176:179], v[44:47]
	v_mfma_f32_16x16x32_bf16 v[40:43], v[160:163], v[176:179], v[40:43]
	v_mfma_f32_16x16x32_bf16 v[28:31], v[152:155], v[186:189], v[28:31]
	v_mfma_f32_16x16x32_bf16 v[24:27], v[160:163], v[186:189], v[24:27]
	v_mfma_f32_16x16x32_bf16 v[12:15], v[152:155], v[194:197], v[12:15]
	v_mfma_f32_16x16x32_bf16 v[8:11], v[160:163], v[194:197], v[8:11]
	v_mfma_f32_16x16x32_bf16 v[60:63], v[156:159], v[172:175], v[60:63]
	v_mfma_f32_16x16x32_bf16 v[56:59], v[164:167], v[172:175], v[56:59]
	v_mfma_f32_16x16x32_bf16 v[44:47], v[156:159], v[180:183], v[44:47]
	v_mfma_f32_16x16x32_bf16 v[40:43], v[164:167], v[180:183], v[40:43]
	v_mfma_f32_16x16x32_bf16 v[28:31], v[156:159], v[190:193], v[28:31]
	v_mfma_f32_16x16x32_bf16 v[24:27], v[164:167], v[190:193], v[24:27]
	v_mfma_f32_16x16x32_bf16 v[12:15], v[156:159], v[198:201], v[12:15]
	v_mfma_f32_16x16x32_bf16 v[8:11], v[164:167], v[198:201], v[8:11]
	s_setprio 0
	s_barrier
	s_add_u32 s34, s28, 0x80080
	s_addc_u32 s35, s29, 0
	s_add_i32 m0, s47, 0x1c000
	s_nop 0
	global_load_lds_dwordx4 v132, s[34:35]
	s_add_i32 m0, s47, 0x1e000
	s_nop 0
	global_load_lds_dwordx4 v128, s[34:35]
	s_waitcnt vmcnt(6)
	s_barrier
	s_setprio 1
	v_mfma_f32_16x16x32_bf16 v[52:55], v[202:205], v[168:171], v[52:55]
	v_mfma_f32_16x16x32_bf16 v[48:51], v[210:213], v[168:171], v[48:51]
	v_mfma_f32_16x16x32_bf16 v[36:39], v[202:205], v[176:179], v[36:39]
	v_mfma_f32_16x16x32_bf16 v[32:35], v[210:213], v[176:179], v[32:35]
	v_mfma_f32_16x16x32_bf16 v[20:23], v[202:205], v[186:189], v[20:23]
	v_mfma_f32_16x16x32_bf16 v[16:19], v[210:213], v[186:189], v[16:19]
	v_mfma_f32_16x16x32_bf16 v[4:7], v[202:205], v[194:197], v[4:7]
	v_mfma_f32_16x16x32_bf16 v[0:3], v[210:213], v[194:197], v[0:3]
	v_mfma_f32_16x16x32_bf16 v[52:55], v[206:209], v[172:175], v[52:55]
	v_mfma_f32_16x16x32_bf16 v[48:51], v[214:217], v[172:175], v[48:51]
	v_mfma_f32_16x16x32_bf16 v[36:39], v[206:209], v[180:183], v[36:39]
	v_mfma_f32_16x16x32_bf16 v[32:35], v[214:217], v[180:183], v[32:35]
	v_mfma_f32_16x16x32_bf16 v[20:23], v[206:209], v[190:193], v[20:23]
	v_mfma_f32_16x16x32_bf16 v[16:19], v[214:217], v[190:193], v[16:19]
	v_mfma_f32_16x16x32_bf16 v[4:7], v[206:209], v[198:201], v[4:7]
	v_mfma_f32_16x16x32_bf16 v[0:3], v[214:217], v[198:201], v[0:3]
	s_setprio 0
	s_add_i32 s59, s59, 2
	s_add_u32 s26, s26, 0x100
	s_addc_u32 s27, s27, 0
	s_add_u32 s57, s57, 0x100
	s_addc_u32 s58, s58, 0
	s_cmp_gt_u32 s59, 29
	s_barrier
	s_cbranch_scc0 .LBB0_1065
	v_mul_f32_e32 v154, 0xbfb8aa3b, v124
	v_exp_f32_e32 v154, v154
	v_mul_f32_e32 v155, 0xbfb8aa3b, v125
	v_exp_f32_e32 v155, v155
	v_lshl_add_u32 v151, s24, 8, v146
	v_add_f32_e32 v154, 1.0, v154
	v_rcp_f32_e32 v154, v154
	v_add_f32_e32 v155, 1.0, v155
	v_rcp_f32_e32 v155, v155
	s_lshl_b32 s24, s13, 7
	v_mul_f32_e32 v124, v124, v154
	v_mul_f32_e32 v120, v120, v124
	v_mul_f32_e32 v124, v125, v155
	v_mul_f32_e32 v125, 0xbfb8aa3b, v126
	v_exp_f32_e32 v125, v125
	v_mul_f32_e32 v154, 0xbfb8aa3b, v127
	v_exp_f32_e32 v154, v154
	v_mul_f32_e32 v121, v121, v124
	v_add_f32_e32 v124, 1.0, v125
	v_rcp_f32_e32 v124, v124
	v_add_f32_e32 v125, 1.0, v154
	v_rcp_f32_e32 v125, v125
	v_cvt_pk_bf16_f32 v120, v120, v121
	v_mul_f32_e32 v121, v126, v124
	v_mul_f32_e32 v121, v122, v121
	v_mul_f32_e32 v122, v127, v125
	v_mul_f32_e32 v122, v123, v122
	v_mul_f32_e32 v123, 0xbfb8aa3b, v116
	v_exp_f32_e32 v123, v123
	v_mul_f32_e32 v124, 0xbfb8aa3b, v117
	v_exp_f32_e32 v124, v124
	v_cvt_pk_bf16_f32 v121, v121, v122
	v_add_f32_e32 v122, 1.0, v123
	v_rcp_f32_e32 v122, v122
	v_add_f32_e32 v123, 1.0, v124
	s_ashr_i32 s25, s24, 31
	v_mov_b64_e32 v[144:145], s[6:7]
	v_rcp_f32_e32 v123, v123
	v_mad_i64_i32 v[152:153], s[26:27], v151, s55, v[144:145]
	s_lshl_b64 s[24:25], s[24:25], 1
	v_lshl_add_u64 v[152:153], v[152:153], 0, s[24:25]
	s_mov_b32 s13, s9
	v_lshl_add_u64 v[152:153], v[152:153], 0, s[12:13]
	v_mul_f32_e32 v116, v116, v122
	v_lshl_add_u64 v[152:153], v[152:153], 0, v[136:137]
	v_mul_f32_e32 v112, v112, v116
	v_mul_f32_e32 v116, v117, v123
	v_mul_f32_e32 v117, 0xbfb8aa3b, v118
	global_store_dwordx2 v[152:153], v[120:121], off
	v_exp_f32_e32 v117, v117
	v_mul_f32_e32 v120, 0xbfb8aa3b, v119
	v_exp_f32_e32 v120, v120
	v_mul_f32_e32 v113, v113, v116
	v_add_f32_e32 v116, 1.0, v117
	v_rcp_f32_e32 v116, v116
	v_add_f32_e32 v117, 1.0, v120
	v_rcp_f32_e32 v117, v117
	v_cvt_pk_bf16_f32 v112, v112, v113
	v_mul_f32_e32 v113, v118, v116
	v_mul_f32_e32 v113, v114, v113
	v_mul_f32_e32 v114, v119, v117
	v_mul_f32_e32 v114, v115, v114
	v_cvt_pk_bf16_f32 v113, v113, v114
	v_mul_f32_e32 v114, 0xbfb8aa3b, v108
	v_exp_f32_e32 v114, v114
	v_mul_f32_e32 v115, 0xbfb8aa3b, v109
	v_exp_f32_e32 v115, v115
	global_store_dwordx2 v[152:153], v[112:113], off offset:128
	v_add_f32_e32 v114, 1.0, v114
	v_rcp_f32_e32 v114, v114
	v_add_f32_e32 v115, 1.0, v115
	v_rcp_f32_e32 v115, v115
	v_or_b32_e32 v112, 16, v151
	v_mul_f32_e32 v108, v108, v114
	v_mul_f32_e32 v104, v104, v108
	v_mul_f32_e32 v108, v109, v115
	v_mul_f32_e32 v109, 0xbfb8aa3b, v110
	v_exp_f32_e32 v109, v109
	v_mul_f32_e32 v114, 0xbfb8aa3b, v111
	v_exp_f32_e32 v114, v114
	v_mul_f32_e32 v105, v105, v108
	v_add_f32_e32 v108, 1.0, v109
	v_rcp_f32_e32 v108, v108
	v_add_f32_e32 v109, 1.0, v114
	v_rcp_f32_e32 v109, v109
	v_cvt_pk_bf16_f32 v104, v104, v105
	v_mul_f32_e32 v105, v110, v108
	v_mul_f32_e32 v105, v106, v105
	v_mul_f32_e32 v106, v111, v109
	v_mul_f32_e32 v106, v107, v106
	v_mul_f32_e32 v107, 0xbfb8aa3b, v100
	v_exp_f32_e32 v107, v107
	v_mul_f32_e32 v108, 0xbfb8aa3b, v101
	v_exp_f32_e32 v108, v108
	v_cvt_pk_bf16_f32 v105, v105, v106
	v_add_f32_e32 v106, 1.0, v107
	v_rcp_f32_e32 v106, v106
	v_add_f32_e32 v107, 1.0, v108
	v_rcp_f32_e32 v107, v107
	v_mad_i64_i32 v[112:113], s[26:27], v112, s55, v[144:145]
	v_lshl_add_u64 v[112:113], v[112:113], 0, s[24:25]
	v_lshl_add_u64 v[112:113], v[112:113], 0, s[12:13]
	v_mul_f32_e32 v100, v100, v106
	v_lshl_add_u64 v[112:113], v[112:113], 0, v[136:137]
	v_mul_f32_e32 v96, v96, v100
	v_mul_f32_e32 v100, v101, v107
	v_mul_f32_e32 v101, 0xbfb8aa3b, v102
	global_store_dwordx2 v[112:113], v[104:105], off
	v_exp_f32_e32 v101, v101
	v_mul_f32_e32 v104, 0xbfb8aa3b, v103
	v_exp_f32_e32 v104, v104
	v_mul_f32_e32 v97, v97, v100
	v_add_f32_e32 v100, 1.0, v101
	v_rcp_f32_e32 v100, v100
	v_add_f32_e32 v101, 1.0, v104
	v_rcp_f32_e32 v101, v101
	v_cvt_pk_bf16_f32 v96, v96, v97
	v_mul_f32_e32 v97, v102, v100
	v_mul_f32_e32 v97, v98, v97
	v_mul_f32_e32 v98, v103, v101
	v_mul_f32_e32 v98, v99, v98
	v_cvt_pk_bf16_f32 v97, v97, v98
	v_mul_f32_e32 v98, 0xbfb8aa3b, v92
	v_exp_f32_e32 v98, v98
	v_mul_f32_e32 v99, 0xbfb8aa3b, v93
	v_exp_f32_e32 v99, v99
	global_store_dwordx2 v[112:113], v[96:97], off offset:128
	v_add_f32_e32 v98, 1.0, v98
	v_rcp_f32_e32 v98, v98
	v_add_f32_e32 v99, 1.0, v99
	v_rcp_f32_e32 v99, v99
	v_or_b32_e32 v96, 32, v151
	v_mul_f32_e32 v92, v92, v98
	v_mul_f32_e32 v88, v88, v92
	v_mul_f32_e32 v92, v93, v99
	v_mul_f32_e32 v93, 0xbfb8aa3b, v94
	v_exp_f32_e32 v93, v93
	v_mul_f32_e32 v98, 0xbfb8aa3b, v95
	v_exp_f32_e32 v98, v98
	v_mul_f32_e32 v89, v89, v92
	v_add_f32_e32 v92, 1.0, v93
	v_rcp_f32_e32 v92, v92
	v_add_f32_e32 v93, 1.0, v98
	v_rcp_f32_e32 v93, v93
	v_cvt_pk_bf16_f32 v88, v88, v89
	v_mul_f32_e32 v89, v94, v92
	v_mul_f32_e32 v89, v90, v89
	v_mul_f32_e32 v90, v95, v93
	v_mul_f32_e32 v90, v91, v90
	v_mul_f32_e32 v91, 0xbfb8aa3b, v84
	v_exp_f32_e32 v91, v91
	v_mul_f32_e32 v92, 0xbfb8aa3b, v85
	v_exp_f32_e32 v92, v92
	v_cvt_pk_bf16_f32 v89, v89, v90
	v_add_f32_e32 v90, 1.0, v91
	v_rcp_f32_e32 v90, v90
	v_add_f32_e32 v91, 1.0, v92
	v_rcp_f32_e32 v91, v91
	v_mad_i64_i32 v[96:97], s[26:27], v96, s55, v[144:145]
	v_lshl_add_u64 v[96:97], v[96:97], 0, s[24:25]
	v_lshl_add_u64 v[96:97], v[96:97], 0, s[12:13]
	v_mul_f32_e32 v84, v84, v90
	v_lshl_add_u64 v[96:97], v[96:97], 0, v[136:137]
	v_mul_f32_e32 v80, v80, v84
	v_mul_f32_e32 v84, v85, v91
	v_mul_f32_e32 v85, 0xbfb8aa3b, v86
	global_store_dwordx2 v[96:97], v[88:89], off
	v_exp_f32_e32 v85, v85
	v_mul_f32_e32 v88, 0xbfb8aa3b, v87
	v_exp_f32_e32 v88, v88
	v_mul_f32_e32 v81, v81, v84
	v_add_f32_e32 v84, 1.0, v85
	v_rcp_f32_e32 v84, v84
	v_add_f32_e32 v85, 1.0, v88
	v_rcp_f32_e32 v85, v85
	v_cvt_pk_bf16_f32 v80, v80, v81
	v_mul_f32_e32 v81, v86, v84
	v_mul_f32_e32 v81, v82, v81
	v_mul_f32_e32 v82, v87, v85
	v_mul_f32_e32 v82, v83, v82
	v_cvt_pk_bf16_f32 v81, v81, v82
	v_mul_f32_e32 v82, 0xbfb8aa3b, v76
	v_exp_f32_e32 v82, v82
	v_mul_f32_e32 v83, 0xbfb8aa3b, v77
	v_exp_f32_e32 v83, v83
	global_store_dwordx2 v[96:97], v[80:81], off offset:128
	v_add_f32_e32 v82, 1.0, v82
	v_rcp_f32_e32 v82, v82
	v_add_f32_e32 v83, 1.0, v83
	v_rcp_f32_e32 v83, v83
	v_or_b32_e32 v80, 48, v151
	v_mul_f32_e32 v76, v76, v82
	v_mul_f32_e32 v72, v72, v76
	v_mul_f32_e32 v76, v77, v83
	v_mul_f32_e32 v77, 0xbfb8aa3b, v78
	v_exp_f32_e32 v77, v77
	v_mul_f32_e32 v82, 0xbfb8aa3b, v79
	v_exp_f32_e32 v82, v82
	v_mul_f32_e32 v73, v73, v76
	v_add_f32_e32 v76, 1.0, v77
	v_rcp_f32_e32 v76, v76
	v_add_f32_e32 v77, 1.0, v82
	v_rcp_f32_e32 v77, v77
	v_cvt_pk_bf16_f32 v72, v72, v73
	v_mul_f32_e32 v73, v78, v76
	v_mul_f32_e32 v73, v74, v73
	v_mul_f32_e32 v74, v79, v77
	v_mul_f32_e32 v74, v75, v74
	v_mul_f32_e32 v75, 0xbfb8aa3b, v68
	v_exp_f32_e32 v75, v75
	v_mul_f32_e32 v76, 0xbfb8aa3b, v69
	v_exp_f32_e32 v76, v76
	v_cvt_pk_bf16_f32 v73, v73, v74
	v_add_f32_e32 v74, 1.0, v75
	v_rcp_f32_e32 v74, v74
	v_add_f32_e32 v75, 1.0, v76
	v_rcp_f32_e32 v75, v75
	v_mad_i64_i32 v[80:81], s[26:27], v80, s55, v[144:145]
	v_lshl_add_u64 v[80:81], v[80:81], 0, s[24:25]
	v_lshl_add_u64 v[80:81], v[80:81], 0, s[12:13]
	v_mul_f32_e32 v68, v68, v74
	v_lshl_add_u64 v[80:81], v[80:81], 0, v[136:137]
	v_mul_f32_e32 v64, v64, v68
	v_mul_f32_e32 v68, v69, v75
	v_mul_f32_e32 v69, 0xbfb8aa3b, v70
	global_store_dwordx2 v[80:81], v[72:73], off
	v_exp_f32_e32 v69, v69
	v_mul_f32_e32 v72, 0xbfb8aa3b, v71
	v_exp_f32_e32 v72, v72
	v_mul_f32_e32 v65, v65, v68
	v_add_f32_e32 v68, 1.0, v69
	v_rcp_f32_e32 v68, v68
	v_add_f32_e32 v69, 1.0, v72
	v_rcp_f32_e32 v69, v69
	v_cvt_pk_bf16_f32 v64, v64, v65
	v_mul_f32_e32 v65, v70, v68
	v_mul_f32_e32 v65, v66, v65
	v_mul_f32_e32 v66, v71, v69
	v_mul_f32_e32 v66, v67, v66
	v_cvt_pk_bf16_f32 v65, v65, v66
	v_mul_f32_e32 v66, 0xbfb8aa3b, v60
	v_exp_f32_e32 v66, v66
	v_mul_f32_e32 v67, 0xbfb8aa3b, v61
	v_exp_f32_e32 v67, v67
	global_store_dwordx2 v[80:81], v[64:65], off offset:128
	v_add_f32_e32 v66, 1.0, v66
	v_rcp_f32_e32 v66, v66
	v_add_f32_e32 v67, 1.0, v67
	v_rcp_f32_e32 v67, v67
	v_add_u32_e32 v64, 0x80, v151
	v_mul_f32_e32 v60, v60, v66
	v_mul_f32_e32 v56, v56, v60
	v_mul_f32_e32 v60, v61, v67
	v_mul_f32_e32 v61, 0xbfb8aa3b, v62
	v_exp_f32_e32 v61, v61
	v_mul_f32_e32 v66, 0xbfb8aa3b, v63
	v_exp_f32_e32 v66, v66
	v_mul_f32_e32 v57, v57, v60
	v_add_f32_e32 v60, 1.0, v61
	v_rcp_f32_e32 v60, v60
	v_add_f32_e32 v61, 1.0, v66
	v_rcp_f32_e32 v61, v61
	v_cvt_pk_bf16_f32 v56, v56, v57
	v_mul_f32_e32 v57, v62, v60
	v_mul_f32_e32 v57, v58, v57
	v_mul_f32_e32 v58, v63, v61
	v_mul_f32_e32 v58, v59, v58
	v_mul_f32_e32 v59, 0xbfb8aa3b, v52
	v_exp_f32_e32 v59, v59
	v_mul_f32_e32 v60, 0xbfb8aa3b, v53
	v_exp_f32_e32 v60, v60
	v_cvt_pk_bf16_f32 v57, v57, v58
	v_add_f32_e32 v58, 1.0, v59
	v_rcp_f32_e32 v58, v58
	v_add_f32_e32 v59, 1.0, v60
	v_rcp_f32_e32 v59, v59
	v_mad_i64_i32 v[64:65], s[26:27], v64, s55, v[144:145]
	v_lshl_add_u64 v[64:65], v[64:65], 0, s[24:25]
	v_lshl_add_u64 v[64:65], v[64:65], 0, s[12:13]
	v_mul_f32_e32 v52, v52, v58
	v_lshl_add_u64 v[64:65], v[64:65], 0, v[136:137]
	v_mul_f32_e32 v48, v48, v52
	v_mul_f32_e32 v52, v53, v59
	v_mul_f32_e32 v53, 0xbfb8aa3b, v54
	global_store_dwordx2 v[64:65], v[56:57], off
	v_exp_f32_e32 v53, v53
	v_mul_f32_e32 v56, 0xbfb8aa3b, v55
	v_exp_f32_e32 v56, v56
	v_mul_f32_e32 v49, v49, v52
	v_add_f32_e32 v52, 1.0, v53
	v_rcp_f32_e32 v52, v52
	v_add_f32_e32 v53, 1.0, v56
	v_rcp_f32_e32 v53, v53
	v_cvt_pk_bf16_f32 v48, v48, v49
	v_mul_f32_e32 v49, v54, v52
	v_mul_f32_e32 v49, v50, v49
	v_mul_f32_e32 v50, v55, v53
	v_mul_f32_e32 v50, v51, v50
	v_cvt_pk_bf16_f32 v49, v49, v50
	v_mul_f32_e32 v50, 0xbfb8aa3b, v44
	v_exp_f32_e32 v50, v50
	v_mul_f32_e32 v51, 0xbfb8aa3b, v45
	v_exp_f32_e32 v51, v51
	global_store_dwordx2 v[64:65], v[48:49], off offset:128
	v_add_f32_e32 v50, 1.0, v50
	v_rcp_f32_e32 v50, v50
	v_add_f32_e32 v51, 1.0, v51
	v_rcp_f32_e32 v51, v51
	v_add_u32_e32 v48, 0x90, v151
	v_mul_f32_e32 v44, v44, v50
	v_mul_f32_e32 v40, v40, v44
	v_mul_f32_e32 v44, v45, v51
	v_mul_f32_e32 v45, 0xbfb8aa3b, v46
	v_exp_f32_e32 v45, v45
	v_mul_f32_e32 v50, 0xbfb8aa3b, v47
	v_exp_f32_e32 v50, v50
	v_mul_f32_e32 v41, v41, v44
	v_add_f32_e32 v44, 1.0, v45
	v_rcp_f32_e32 v44, v44
	v_add_f32_e32 v45, 1.0, v50
	v_rcp_f32_e32 v45, v45
	v_cvt_pk_bf16_f32 v40, v40, v41
	v_mul_f32_e32 v41, v46, v44
	v_mul_f32_e32 v41, v42, v41
	v_mul_f32_e32 v42, v47, v45
	v_mul_f32_e32 v42, v43, v42
	v_mul_f32_e32 v43, 0xbfb8aa3b, v36
	v_exp_f32_e32 v43, v43
	v_mul_f32_e32 v44, 0xbfb8aa3b, v37
	v_exp_f32_e32 v44, v44
	v_cvt_pk_bf16_f32 v41, v41, v42
	v_add_f32_e32 v42, 1.0, v43
	v_rcp_f32_e32 v42, v42
	v_add_f32_e32 v43, 1.0, v44
	v_rcp_f32_e32 v43, v43
	v_mad_i64_i32 v[48:49], s[26:27], v48, s55, v[144:145]
	v_lshl_add_u64 v[48:49], v[48:49], 0, s[24:25]
	v_lshl_add_u64 v[48:49], v[48:49], 0, s[12:13]
	v_mul_f32_e32 v36, v36, v42
	v_lshl_add_u64 v[48:49], v[48:49], 0, v[136:137]
	v_mul_f32_e32 v32, v32, v36
	v_mul_f32_e32 v36, v37, v43
	v_mul_f32_e32 v37, 0xbfb8aa3b, v38
	global_store_dwordx2 v[48:49], v[40:41], off
	v_exp_f32_e32 v37, v37
	v_mul_f32_e32 v40, 0xbfb8aa3b, v39
	v_exp_f32_e32 v40, v40
	v_mul_f32_e32 v33, v33, v36
	v_add_f32_e32 v36, 1.0, v37
	v_rcp_f32_e32 v36, v36
	v_add_f32_e32 v37, 1.0, v40
	v_rcp_f32_e32 v37, v37
	v_cvt_pk_bf16_f32 v32, v32, v33
	v_mul_f32_e32 v33, v38, v36
	v_mul_f32_e32 v33, v34, v33
	v_mul_f32_e32 v34, v39, v37
	v_mul_f32_e32 v34, v35, v34
	v_cvt_pk_bf16_f32 v33, v33, v34
	v_mul_f32_e32 v34, 0xbfb8aa3b, v28
	v_exp_f32_e32 v34, v34
	v_mul_f32_e32 v35, 0xbfb8aa3b, v29
	v_exp_f32_e32 v35, v35
	global_store_dwordx2 v[48:49], v[32:33], off offset:128
	v_add_f32_e32 v34, 1.0, v34
	v_rcp_f32_e32 v34, v34
	v_add_f32_e32 v35, 1.0, v35
	v_rcp_f32_e32 v35, v35
	v_add_u32_e32 v32, 0xa0, v151
	v_mul_f32_e32 v28, v28, v34
	v_mul_f32_e32 v24, v24, v28
	v_mul_f32_e32 v28, v29, v35
	v_mul_f32_e32 v29, 0xbfb8aa3b, v30
	v_exp_f32_e32 v29, v29
	v_mul_f32_e32 v34, 0xbfb8aa3b, v31
	v_exp_f32_e32 v34, v34
	v_mul_f32_e32 v25, v25, v28
	v_add_f32_e32 v28, 1.0, v29
	v_rcp_f32_e32 v28, v28
	v_add_f32_e32 v29, 1.0, v34
	v_rcp_f32_e32 v29, v29
	v_cvt_pk_bf16_f32 v24, v24, v25
	v_mul_f32_e32 v25, v30, v28
	v_mul_f32_e32 v25, v26, v25
	v_mul_f32_e32 v26, v31, v29
	v_mul_f32_e32 v26, v27, v26
	v_mul_f32_e32 v27, 0xbfb8aa3b, v20
	v_exp_f32_e32 v27, v27
	v_mul_f32_e32 v28, 0xbfb8aa3b, v21
	v_exp_f32_e32 v28, v28
	v_cvt_pk_bf16_f32 v25, v25, v26
	v_add_f32_e32 v26, 1.0, v27
	v_rcp_f32_e32 v26, v26
	v_add_f32_e32 v27, 1.0, v28
	v_rcp_f32_e32 v27, v27
	v_mad_i64_i32 v[32:33], s[26:27], v32, s55, v[144:145]
	v_lshl_add_u64 v[32:33], v[32:33], 0, s[24:25]
	v_lshl_add_u64 v[32:33], v[32:33], 0, s[12:13]
	v_mul_f32_e32 v20, v20, v26
	v_lshl_add_u64 v[32:33], v[32:33], 0, v[136:137]
	v_mul_f32_e32 v16, v16, v20
	v_mul_f32_e32 v20, v21, v27
	v_mul_f32_e32 v21, 0xbfb8aa3b, v22
	global_store_dwordx2 v[32:33], v[24:25], off
	v_exp_f32_e32 v21, v21
	v_mul_f32_e32 v24, 0xbfb8aa3b, v23
	v_exp_f32_e32 v24, v24
	v_mul_f32_e32 v17, v17, v20
	v_add_f32_e32 v20, 1.0, v21
	v_rcp_f32_e32 v20, v20
	v_add_f32_e32 v21, 1.0, v24
	v_rcp_f32_e32 v21, v21
	v_cvt_pk_bf16_f32 v16, v16, v17
	v_mul_f32_e32 v17, v22, v20
	v_mul_f32_e32 v17, v18, v17
	v_mul_f32_e32 v18, v23, v21
	v_mul_f32_e32 v18, v19, v18
	v_cvt_pk_bf16_f32 v17, v17, v18
	v_mul_f32_e32 v18, 0xbfb8aa3b, v12
	v_exp_f32_e32 v18, v18
	v_mul_f32_e32 v19, 0xbfb8aa3b, v13
	v_exp_f32_e32 v19, v19
	global_store_dwordx2 v[32:33], v[16:17], off offset:128
	v_add_f32_e32 v18, 1.0, v18
	v_rcp_f32_e32 v18, v18
	v_add_f32_e32 v19, 1.0, v19
	v_rcp_f32_e32 v19, v19
	v_add_u32_e32 v16, 0xb0, v151
	v_mul_f32_e32 v12, v12, v18
	v_mul_f32_e32 v8, v8, v12
	v_mul_f32_e32 v12, v13, v19
	v_mul_f32_e32 v13, 0xbfb8aa3b, v14
	v_exp_f32_e32 v13, v13
	v_mul_f32_e32 v18, 0xbfb8aa3b, v15
	v_exp_f32_e32 v18, v18
	v_mul_f32_e32 v9, v9, v12
	v_add_f32_e32 v12, 1.0, v13
	v_rcp_f32_e32 v12, v12
	v_add_f32_e32 v13, 1.0, v18
	v_rcp_f32_e32 v13, v13
	v_cvt_pk_bf16_f32 v8, v8, v9
	v_mul_f32_e32 v9, v14, v12
	v_mul_f32_e32 v9, v10, v9
	v_mul_f32_e32 v10, v15, v13
	v_mul_f32_e32 v10, v11, v10
	v_mul_f32_e32 v11, 0xbfb8aa3b, v4
	v_exp_f32_e32 v11, v11
	v_mul_f32_e32 v12, 0xbfb8aa3b, v5
	v_exp_f32_e32 v12, v12
	v_cvt_pk_bf16_f32 v9, v9, v10
	v_add_f32_e32 v10, 1.0, v11
	v_rcp_f32_e32 v10, v10
	v_add_f32_e32 v11, 1.0, v12
	v_rcp_f32_e32 v11, v11
	v_mad_i64_i32 v[16:17], s[26:27], v16, s55, v[144:145]
	v_lshl_add_u64 v[16:17], v[16:17], 0, s[24:25]
	v_lshl_add_u64 v[16:17], v[16:17], 0, s[12:13]
	v_mul_f32_e32 v4, v4, v10
	v_lshl_add_u64 v[16:17], v[16:17], 0, v[136:137]
	v_mul_f32_e32 v0, v0, v4
	v_mul_f32_e32 v4, v5, v11
	v_mul_f32_e32 v5, 0xbfb8aa3b, v6
	global_store_dwordx2 v[16:17], v[8:9], off
	v_exp_f32_e32 v5, v5
	v_mul_f32_e32 v8, 0xbfb8aa3b, v7
	v_exp_f32_e32 v8, v8
	v_mul_f32_e32 v1, v1, v4
	v_add_f32_e32 v4, 1.0, v5
	v_rcp_f32_e32 v4, v4
	v_add_f32_e32 v5, 1.0, v8
	v_rcp_f32_e32 v5, v5
	v_cvt_pk_bf16_f32 v0, v0, v1
	v_mul_f32_e32 v1, v6, v4
	v_mul_f32_e32 v1, v2, v1
	v_mul_f32_e32 v2, v7, v5
	s_and_b64 vcc, exec, s[18:19]
	s_mov_b32 s13, s16
	s_mov_b32 s24, s14
	s_mov_b64 s[28:29], s[22:23]
	s_mov_b64 s[26:27], s[20:21]
	v_mul_f32_e32 v2, v3, v2
	v_cvt_pk_bf16_f32 v1, v1, v2
	global_store_dwordx2 v[16:17], v[0:1], off offset:128
	s_cbranch_vccz .LBB0_1062
	s_waitcnt vmcnt(0)
	s_cmpk_gt_u32 s2, 0xff
	s_cbranch_scc1 .LBB0_1069
	s_barrier

.LBB0_1151:
	v_lshlrev_b64 v[98:99], 5, v[96:97]
	s_barrier
	global_load_dwordx4 v[200:203], v[158:159], off
	global_load_dwordx4 v[204:207], v[158:159], off offset:64
	global_load_dwordx4 v[208:211], v[158:159], off offset:512
	global_load_dwordx4 v[212:215], v[158:159], off offset:576
	v_lshl_add_u64 v[98:99], s[10:11], 0, v[98:99]
	global_load_dwordx2 v[102:103], v[98:99], off sc1
	global_load_dwordx2 v[104:105], v[98:99], off offset:8 sc1
	global_load_dwordx2 v[106:107], v[98:99], off offset:16 sc1
	global_load_dwordx2 v[108:109], v[98:99], off offset:24 sc1
	s_waitcnt lgkmcnt(0)
	s_mov_b32 s30, 64
	s_mov_b64 s[28:29], 0
	s_mov_b32 s70, s69
	s_waitcnt vmcnt(3)
	v_add_f32_e32 v102, v102, v103
	s_waitcnt vmcnt(2)
	v_add_f32_e32 v103, v104, v105
	v_add_f32_e32 v102, 0, v102
	s_waitcnt vmcnt(1)
	v_add_f32_e32 v104, v106, v107
	v_add_f32_e32 v102, v102, v103
	s_waitcnt vmcnt(0)
	v_add_f32_e32 v105, v108, v109
	v_add_f32_e32 v102, v102, v104
	v_add_f32_e32 v102, v102, v105
	v_fmamk_f32 v102, v102, 0x3a000000, v191
	v_mul_f32_e32 v103, 0x4f800000, v102
	v_cmp_gt_f32_e32 vcc, s67, v102
	s_nop 1
	v_cndmask_b32_e32 v104, v102, v103, vcc
	v_sqrt_f32_e32 v105, v104
	v_lshlrev_b64 v[102:103], 13, v[96:97]
	v_lshl_add_u64 v[102:103], v[160:161], 0, v[102:103]
	v_add_u32_e32 v97, -1, v105
	v_add_u32_e32 v106, 1, v105
	v_fma_f32 v107, -v97, v105, v104
	v_fma_f32 v108, -v106, v105, v104
	v_cmp_ge_f32_e64 s[4:5], 0, v107
	s_nop 1
	v_cndmask_b32_e64 v97, v105, v97, s[4:5]
	v_cmp_lt_f32_e64 s[4:5], 0, v108
	s_nop 1
	v_cndmask_b32_e64 v97, v97, v106, s[4:5]
	v_mul_f32_e32 v105, 0x37800000, v97
	v_cndmask_b32_e32 v97, v97, v105, vcc
	v_cmp_class_f32_e32 vcc, v104, v192
	s_nop 1
	v_cndmask_b32_e32 v97, v97, v104, vcc
	v_div_scale_f32 v104, s[4:5], v97, v97, 1.0
	v_rcp_f32_e32 v105, v104
	v_div_scale_f32 v106, vcc, 1.0, v97, 1.0
	v_fma_f32 v107, -v104, v105, 1.0
	v_fmac_f32_e32 v105, v107, v105
	v_mul_f32_e32 v107, v106, v105
	v_fma_f32 v108, -v104, v107, v106
	v_fmac_f32_e32 v107, v108, v105
	v_fma_f32 v104, -v104, v107, v106
	v_div_fmas_f32 v104, v104, v105, v107
	v_div_fixup_f32 v104, v104, v97, 1.0
	v_pk_mul_f32 v[92:93], v[92:93], v[104:105] op_sel_hi:[1,0]
	v_pk_mul_f32 v[94:95], v[94:95], v[104:105] op_sel_hi:[1,0]
	v_pk_mul_f32 v[92:93], v[200:201], v[92:93]
	v_pk_mul_f32 v[94:95], v[202:203], v[94:95]
	global_store_dwordx4 v[102:103], v[92:95], off
	v_pk_mul_f32 v[90:91], v[90:91], v[104:105] op_sel_hi:[1,0]
	v_pk_mul_f32 v[88:89], v[88:89], v[104:105] op_sel_hi:[1,0]
	v_pk_mul_f32 v[86:87], v[86:87], v[104:105] op_sel_hi:[1,0]
	v_pk_mul_f32 v[84:85], v[84:85], v[104:105] op_sel_hi:[1,0]
	v_pk_mul_f32 v[82:83], v[82:83], v[104:105] op_sel_hi:[1,0]
	v_pk_mul_f32 v[80:81], v[80:81], v[104:105] op_sel_hi:[1,0]
	v_pk_mul_f32 v[88:89], v[204:205], v[88:89]
	v_pk_mul_f32 v[90:91], v[206:207], v[90:91]
	global_store_dwordx4 v[102:103], v[88:91], off offset:64
	v_pk_mul_f32 v[84:85], v[208:209], v[84:85]
	v_pk_mul_f32 v[86:87], v[210:211], v[86:87]
	global_store_dwordx4 v[102:103], v[84:87], off offset:512
	v_add_u32_e32 v88, 16, v96
	v_ashrrev_i32_e32 v89, 31, v88
	v_lshlrev_b64 v[90:91], 5, v[88:89]
	v_lshl_add_u64 v[90:91], s[10:11], 0, v[90:91]
	v_pk_mul_f32 v[80:81], v[212:213], v[80:81]
	v_pk_mul_f32 v[82:83], v[214:215], v[82:83]
	global_store_dwordx4 v[102:103], v[80:83], off offset:576
	s_nop 0
	global_load_dwordx2 v[84:85], v[90:91], off sc1
	global_load_dwordx2 v[86:87], v[90:91], off offset:8 sc1
	global_load_dwordx2 v[92:93], v[90:91], off offset:16 sc1
	s_nop 0
	global_load_dwordx2 v[90:91], v[90:91], off offset:24 sc1
	s_waitcnt vmcnt(3)
	v_add_f32_e32 v84, v84, v85
	s_waitcnt vmcnt(2)
	v_add_f32_e32 v85, v86, v87
	v_add_f32_e32 v84, 0, v84
	s_waitcnt vmcnt(1)
	v_add_f32_e32 v86, v92, v93
	v_add_f32_e32 v84, v84, v85
	s_waitcnt vmcnt(0)
	v_add_f32_e32 v87, v90, v91
	v_add_f32_e32 v84, v84, v86
	v_add_f32_e32 v84, v84, v87
	v_fmamk_f32 v84, v84, 0x3a000000, v191
	v_mul_f32_e32 v85, 0x4f800000, v84
	v_cmp_gt_f32_e32 vcc, s67, v84
	s_nop 1
	v_cndmask_b32_e32 v86, v84, v85, vcc
	v_sqrt_f32_e32 v87, v86
	v_lshlrev_b64 v[84:85], 13, v[88:89]
	v_lshl_add_u64 v[84:85], v[160:161], 0, v[84:85]
	v_add_u32_e32 v88, -1, v87
	v_add_u32_e32 v89, 1, v87
	v_fma_f32 v90, -v88, v87, v86
	v_fma_f32 v91, -v89, v87, v86
	v_cmp_ge_f32_e64 s[4:5], 0, v90
	s_nop 1
	v_cndmask_b32_e64 v87, v87, v88, s[4:5]
	v_cmp_lt_f32_e64 s[4:5], 0, v91
	s_nop 1
	v_cndmask_b32_e64 v87, v87, v89, s[4:5]
	v_mul_f32_e32 v88, 0x37800000, v87
	v_cndmask_b32_e32 v87, v87, v88, vcc
	v_cmp_class_f32_e32 vcc, v86, v192
	s_nop 1
	v_cndmask_b32_e32 v86, v87, v86, vcc
	v_div_scale_f32 v87, s[4:5], v86, v86, 1.0
	v_rcp_f32_e32 v88, v87
	v_div_scale_f32 v89, vcc, 1.0, v86, 1.0
	v_fma_f32 v90, -v87, v88, 1.0
	v_fmac_f32_e32 v88, v90, v88
	v_mul_f32_e32 v90, v89, v88
	v_fma_f32 v91, -v87, v90, v89
	v_fmac_f32_e32 v90, v91, v88
	v_fma_f32 v87, -v87, v90, v89
	v_div_fmas_f32 v87, v87, v88, v90
	v_div_fixup_f32 v86, v87, v86, 1.0
	v_pk_mul_f32 v[76:77], v[76:77], v[86:87] op_sel_hi:[1,0]
	v_pk_mul_f32 v[78:79], v[78:79], v[86:87] op_sel_hi:[1,0]
	v_pk_mul_f32 v[76:77], v[200:201], v[76:77]
	v_pk_mul_f32 v[78:79], v[202:203], v[78:79]
	global_store_dwordx4 v[84:85], v[76:79], off
	v_pk_mul_f32 v[74:75], v[74:75], v[86:87] op_sel_hi:[1,0]
	v_pk_mul_f32 v[72:73], v[72:73], v[86:87] op_sel_hi:[1,0]
	v_pk_mul_f32 v[70:71], v[70:71], v[86:87] op_sel_hi:[1,0]
	v_pk_mul_f32 v[68:69], v[68:69], v[86:87] op_sel_hi:[1,0]
	v_pk_mul_f32 v[66:67], v[66:67], v[86:87] op_sel_hi:[1,0]
	v_pk_mul_f32 v[64:65], v[64:65], v[86:87] op_sel_hi:[1,0]
	v_pk_mul_f32 v[72:73], v[204:205], v[72:73]
	v_pk_mul_f32 v[74:75], v[206:207], v[74:75]
	global_store_dwordx4 v[84:85], v[72:75], off offset:64
	v_pk_mul_f32 v[68:69], v[208:209], v[68:69]
	v_pk_mul_f32 v[70:71], v[210:211], v[70:71]
	global_store_dwordx4 v[84:85], v[68:71], off offset:512
	v_add_u32_e32 v72, 32, v96
	v_ashrrev_i32_e32 v73, 31, v72
	v_lshlrev_b64 v[74:75], 5, v[72:73]
	v_lshl_add_u64 v[74:75], s[10:11], 0, v[74:75]
	v_pk_mul_f32 v[64:65], v[212:213], v[64:65]
	v_pk_mul_f32 v[66:67], v[214:215], v[66:67]
	global_store_dwordx4 v[84:85], v[64:67], off offset:576
	s_nop 0
	global_load_dwordx2 v[68:69], v[74:75], off sc1
	global_load_dwordx2 v[70:71], v[74:75], off offset:8 sc1
	global_load_dwordx2 v[76:77], v[74:75], off offset:16 sc1
	s_nop 0
	global_load_dwordx2 v[74:75], v[74:75], off offset:24 sc1
	s_waitcnt vmcnt(3)
	v_add_f32_e32 v68, v68, v69
	s_waitcnt vmcnt(2)
	v_add_f32_e32 v69, v70, v71
	v_add_f32_e32 v68, 0, v68
	s_waitcnt vmcnt(1)
	v_add_f32_e32 v70, v76, v77
	v_add_f32_e32 v68, v68, v69
	s_waitcnt vmcnt(0)
	v_add_f32_e32 v71, v74, v75
	v_add_f32_e32 v68, v68, v70
	v_add_f32_e32 v68, v68, v71
	v_fmamk_f32 v68, v68, 0x3a000000, v191
	v_mul_f32_e32 v69, 0x4f800000, v68
	v_cmp_gt_f32_e32 vcc, s67, v68
	s_nop 1
	v_cndmask_b32_e32 v70, v68, v69, vcc
	v_sqrt_f32_e32 v71, v70
	v_lshlrev_b64 v[68:69], 13, v[72:73]
	v_lshl_add_u64 v[68:69], v[160:161], 0, v[68:69]
	v_add_u32_e32 v72, -1, v71
	v_add_u32_e32 v73, 1, v71
	v_fma_f32 v74, -v72, v71, v70
	v_fma_f32 v75, -v73, v71, v70
	v_cmp_ge_f32_e64 s[4:5], 0, v74
	s_nop 1
	v_cndmask_b32_e64 v71, v71, v72, s[4:5]
	v_cmp_lt_f32_e64 s[4:5], 0, v75
	s_nop 1
	v_cndmask_b32_e64 v71, v71, v73, s[4:5]
	v_mul_f32_e32 v72, 0x37800000, v71
	v_cndmask_b32_e32 v71, v71, v72, vcc
	v_cmp_class_f32_e32 vcc, v70, v192
	s_nop 1
	v_cndmask_b32_e32 v70, v71, v70, vcc
	v_div_scale_f32 v71, s[4:5], v70, v70, 1.0
	v_rcp_f32_e32 v72, v71
	v_div_scale_f32 v73, vcc, 1.0, v70, 1.0
	v_fma_f32 v74, -v71, v72, 1.0
	v_fmac_f32_e32 v72, v74, v72
	v_mul_f32_e32 v74, v73, v72
	v_fma_f32 v75, -v71, v74, v73
	v_fmac_f32_e32 v74, v75, v72
	v_fma_f32 v71, -v71, v74, v73
	v_div_fmas_f32 v71, v71, v72, v74
	v_div_fixup_f32 v70, v71, v70, 1.0
	v_pk_mul_f32 v[60:61], v[60:61], v[70:71] op_sel_hi:[1,0]
	v_pk_mul_f32 v[62:63], v[62:63], v[70:71] op_sel_hi:[1,0]
	v_pk_mul_f32 v[60:61], v[200:201], v[60:61]
	v_pk_mul_f32 v[62:63], v[202:203], v[62:63]
	global_store_dwordx4 v[68:69], v[60:63], off
	v_pk_mul_f32 v[58:59], v[58:59], v[70:71] op_sel_hi:[1,0]
	v_pk_mul_f32 v[56:57], v[56:57], v[70:71] op_sel_hi:[1,0]
	v_pk_mul_f32 v[54:55], v[54:55], v[70:71] op_sel_hi:[1,0]
	v_pk_mul_f32 v[52:53], v[52:53], v[70:71] op_sel_hi:[1,0]
	v_pk_mul_f32 v[50:51], v[50:51], v[70:71] op_sel_hi:[1,0]
	v_pk_mul_f32 v[48:49], v[48:49], v[70:71] op_sel_hi:[1,0]
	v_pk_mul_f32 v[56:57], v[204:205], v[56:57]
	v_pk_mul_f32 v[58:59], v[206:207], v[58:59]
	global_store_dwordx4 v[68:69], v[56:59], off offset:64
	v_pk_mul_f32 v[52:53], v[208:209], v[52:53]
	v_pk_mul_f32 v[54:55], v[210:211], v[54:55]
	global_store_dwordx4 v[68:69], v[52:55], off offset:512
	v_add_u32_e32 v56, 0x60, v96
	v_ashrrev_i32_e32 v57, 31, v56
	v_lshlrev_b64 v[58:59], 5, v[56:57]
	v_lshl_add_u64 v[58:59], s[10:11], 0, v[58:59]
	v_pk_mul_f32 v[48:49], v[212:213], v[48:49]
	v_pk_mul_f32 v[50:51], v[214:215], v[50:51]
	global_store_dwordx4 v[68:69], v[48:51], off offset:576
	global_load_dwordx2 v[52:53], v[58:59], off sc1
	global_load_dwordx2 v[54:55], v[58:59], off offset:8 sc1
	global_load_dwordx2 v[60:61], v[58:59], off offset:16 sc1
	s_nop 0
	global_load_dwordx2 v[58:59], v[58:59], off offset:24 sc1
	s_nop 0
	s_waitcnt vmcnt(3)
	v_add_f32_e32 v52, v52, v53
	s_waitcnt vmcnt(2)
	v_add_f32_e32 v53, v54, v55
	v_add_f32_e32 v52, 0, v52
	s_waitcnt vmcnt(1)
	v_add_f32_e32 v54, v60, v61
	v_add_f32_e32 v52, v52, v53
	s_waitcnt vmcnt(0)
	v_add_f32_e32 v55, v58, v59
	v_add_f32_e32 v52, v52, v54
	v_add_f32_e32 v52, v52, v55
	v_fmamk_f32 v52, v52, 0x3a000000, v191
	v_mul_f32_e32 v53, 0x4f800000, v52
	v_cmp_gt_f32_e32 vcc, s67, v52
	s_nop 1
	v_cndmask_b32_e32 v54, v52, v53, vcc
	v_sqrt_f32_e32 v55, v54
	v_lshlrev_b64 v[52:53], 13, v[56:57]
	v_lshl_add_u64 v[52:53], v[160:161], 0, v[52:53]
	v_add_u32_e32 v56, -1, v55
	v_add_u32_e32 v57, 1, v55
	v_fma_f32 v58, -v56, v55, v54
	v_fma_f32 v59, -v57, v55, v54
	v_cmp_ge_f32_e64 s[4:5], 0, v58
	s_nop 1
	v_cndmask_b32_e64 v55, v55, v56, s[4:5]
	v_cmp_lt_f32_e64 s[4:5], 0, v59
	s_nop 1
	v_cndmask_b32_e64 v55, v55, v57, s[4:5]
	v_mul_f32_e32 v56, 0x37800000, v55
	v_cndmask_b32_e32 v55, v55, v56, vcc
	v_cmp_class_f32_e32 vcc, v54, v192
	s_nop 1
	v_cndmask_b32_e32 v54, v55, v54, vcc
	v_div_scale_f32 v55, s[4:5], v54, v54, 1.0
	v_rcp_f32_e32 v56, v55
	v_div_scale_f32 v57, vcc, 1.0, v54, 1.0
	v_fma_f32 v58, -v55, v56, 1.0
	v_fmac_f32_e32 v56, v58, v56
	v_mul_f32_e32 v58, v57, v56
	v_fma_f32 v59, -v55, v58, v57
	v_fmac_f32_e32 v58, v59, v56
	v_fma_f32 v55, -v55, v58, v57
	v_div_fmas_f32 v55, v55, v56, v58
	v_div_fixup_f32 v54, v55, v54, 1.0
	v_pk_mul_f32 v[44:45], v[44:45], v[54:55] op_sel_hi:[1,0]
	v_pk_mul_f32 v[46:47], v[46:47], v[54:55] op_sel_hi:[1,0]
	v_pk_mul_f32 v[44:45], v[200:201], v[44:45]
	v_pk_mul_f32 v[46:47], v[202:203], v[46:47]
	global_store_dwordx4 v[52:53], v[44:47], off
	v_pk_mul_f32 v[42:43], v[42:43], v[54:55] op_sel_hi:[1,0]
	v_pk_mul_f32 v[40:41], v[40:41], v[54:55] op_sel_hi:[1,0]
	v_pk_mul_f32 v[38:39], v[38:39], v[54:55] op_sel_hi:[1,0]
	v_pk_mul_f32 v[36:37], v[36:37], v[54:55] op_sel_hi:[1,0]
	v_pk_mul_f32 v[34:35], v[34:35], v[54:55] op_sel_hi:[1,0]
	v_pk_mul_f32 v[32:33], v[32:33], v[54:55] op_sel_hi:[1,0]
	v_pk_mul_f32 v[40:41], v[204:205], v[40:41]
	v_pk_mul_f32 v[42:43], v[206:207], v[42:43]
	global_store_dwordx4 v[52:53], v[40:43], off offset:64
	v_pk_mul_f32 v[36:37], v[208:209], v[36:37]
	v_pk_mul_f32 v[38:39], v[210:211], v[38:39]
	global_store_dwordx4 v[52:53], v[36:39], off offset:512
	v_add_u32_e32 v40, 0x70, v96
	v_ashrrev_i32_e32 v41, 31, v40
	v_lshlrev_b64 v[42:43], 5, v[40:41]
	v_lshl_add_u64 v[42:43], s[10:11], 0, v[42:43]
	v_pk_mul_f32 v[32:33], v[212:213], v[32:33]
	v_pk_mul_f32 v[34:35], v[214:215], v[34:35]
	global_store_dwordx4 v[52:53], v[32:35], off offset:576
	s_nop 0
	global_load_dwordx2 v[36:37], v[42:43], off sc1
	global_load_dwordx2 v[38:39], v[42:43], off offset:8 sc1
	global_load_dwordx2 v[44:45], v[42:43], off offset:16 sc1
	s_nop 0
	global_load_dwordx2 v[42:43], v[42:43], off offset:24 sc1
	s_waitcnt vmcnt(3)
	v_add_f32_e32 v36, v36, v37
	s_waitcnt vmcnt(2)
	v_add_f32_e32 v37, v38, v39
	v_add_f32_e32 v36, 0, v36
	s_waitcnt vmcnt(1)
	v_add_f32_e32 v38, v44, v45
	v_add_f32_e32 v36, v36, v37
	s_waitcnt vmcnt(0)
	v_add_f32_e32 v39, v42, v43
	v_add_f32_e32 v36, v36, v38
	v_add_f32_e32 v36, v36, v39
	v_fmamk_f32 v36, v36, 0x3a000000, v191
	v_mul_f32_e32 v37, 0x4f800000, v36
	v_cmp_gt_f32_e32 vcc, s67, v36
	s_nop 1
	v_cndmask_b32_e32 v38, v36, v37, vcc
	v_sqrt_f32_e32 v39, v38
	v_lshlrev_b64 v[36:37], 13, v[40:41]
	v_lshl_add_u64 v[36:37], v[160:161], 0, v[36:37]
	v_add_u32_e32 v40, -1, v39
	v_add_u32_e32 v41, 1, v39
	v_fma_f32 v42, -v40, v39, v38
	v_fma_f32 v43, -v41, v39, v38
	v_cmp_ge_f32_e64 s[4:5], 0, v42
	s_nop 1
	v_cndmask_b32_e64 v39, v39, v40, s[4:5]
	v_cmp_lt_f32_e64 s[4:5], 0, v43
	s_nop 1
	v_cndmask_b32_e64 v39, v39, v41, s[4:5]
	v_mul_f32_e32 v40, 0x37800000, v39
	v_cndmask_b32_e32 v39, v39, v40, vcc
	v_cmp_class_f32_e32 vcc, v38, v192
	s_nop 1
	v_cndmask_b32_e32 v38, v39, v38, vcc
	v_div_scale_f32 v39, s[4:5], v38, v38, 1.0
	v_rcp_f32_e32 v40, v39
	v_div_scale_f32 v41, vcc, 1.0, v38, 1.0
	v_fma_f32 v42, -v39, v40, 1.0
	v_fmac_f32_e32 v40, v42, v40
	v_mul_f32_e32 v42, v41, v40
	v_fma_f32 v43, -v39, v42, v41
	v_fmac_f32_e32 v42, v43, v40
	v_fma_f32 v39, -v39, v42, v41
	v_div_fmas_f32 v39, v39, v40, v42
	v_div_fixup_f32 v38, v39, v38, 1.0
	v_pk_mul_f32 v[28:29], v[28:29], v[38:39] op_sel_hi:[1,0]
	v_pk_mul_f32 v[30:31], v[30:31], v[38:39] op_sel_hi:[1,0]
	v_pk_mul_f32 v[28:29], v[200:201], v[28:29]
	v_pk_mul_f32 v[30:31], v[202:203], v[30:31]
	global_store_dwordx4 v[36:37], v[28:31], off
	v_pk_mul_f32 v[26:27], v[26:27], v[38:39] op_sel_hi:[1,0]
	v_pk_mul_f32 v[24:25], v[24:25], v[38:39] op_sel_hi:[1,0]
	v_pk_mul_f32 v[22:23], v[22:23], v[38:39] op_sel_hi:[1,0]
	v_pk_mul_f32 v[20:21], v[20:21], v[38:39] op_sel_hi:[1,0]
	v_pk_mul_f32 v[18:19], v[18:19], v[38:39] op_sel_hi:[1,0]
	v_pk_mul_f32 v[16:17], v[16:17], v[38:39] op_sel_hi:[1,0]
	v_pk_mul_f32 v[24:25], v[204:205], v[24:25]
	v_pk_mul_f32 v[26:27], v[206:207], v[26:27]
	global_store_dwordx4 v[36:37], v[24:27], off offset:64
	v_pk_mul_f32 v[20:21], v[208:209], v[20:21]
	v_pk_mul_f32 v[22:23], v[210:211], v[22:23]
	global_store_dwordx4 v[36:37], v[20:23], off offset:512
	v_add_u32_e32 v24, 0x80, v96
	v_ashrrev_i32_e32 v25, 31, v24
	v_lshlrev_b64 v[26:27], 5, v[24:25]
	v_lshl_add_u64 v[26:27], s[10:11], 0, v[26:27]
	v_pk_mul_f32 v[16:17], v[212:213], v[16:17]
	v_pk_mul_f32 v[18:19], v[214:215], v[18:19]
	global_store_dwordx4 v[36:37], v[16:19], off offset:576
	s_nop 0
	global_load_dwordx2 v[20:21], v[26:27], off sc1
	global_load_dwordx2 v[22:23], v[26:27], off offset:8 sc1
	global_load_dwordx2 v[28:29], v[26:27], off offset:16 sc1
	s_nop 0
	global_load_dwordx2 v[26:27], v[26:27], off offset:24 sc1
	s_waitcnt vmcnt(3)
	v_add_f32_e32 v20, v20, v21
	s_waitcnt vmcnt(2)
	v_add_f32_e32 v21, v22, v23
	v_add_f32_e32 v20, 0, v20
	s_waitcnt vmcnt(1)
	v_add_f32_e32 v22, v28, v29
	v_add_f32_e32 v20, v20, v21
	s_waitcnt vmcnt(0)
	v_add_f32_e32 v23, v26, v27
	v_add_f32_e32 v20, v20, v22
	v_add_f32_e32 v20, v20, v23
	v_fmamk_f32 v20, v20, 0x3a000000, v191
	v_mul_f32_e32 v21, 0x4f800000, v20
	v_cmp_gt_f32_e32 vcc, s67, v20
	s_nop 1
	v_cndmask_b32_e32 v22, v20, v21, vcc
	v_sqrt_f32_e32 v23, v22
	v_lshlrev_b64 v[20:21], 13, v[24:25]
	v_lshl_add_u64 v[20:21], v[160:161], 0, v[20:21]
	v_add_u32_e32 v24, -1, v23
	v_add_u32_e32 v25, 1, v23
	v_fma_f32 v26, -v24, v23, v22
	v_fma_f32 v27, -v25, v23, v22
	v_cmp_ge_f32_e64 s[4:5], 0, v26
	s_nop 1
	v_cndmask_b32_e64 v23, v23, v24, s[4:5]
	v_cmp_lt_f32_e64 s[4:5], 0, v27
	s_nop 1
	v_cndmask_b32_e64 v23, v23, v25, s[4:5]
	v_mul_f32_e32 v24, 0x37800000, v23
	v_cndmask_b32_e32 v23, v23, v24, vcc
	v_cmp_class_f32_e32 vcc, v22, v192
	s_nop 1
	v_cndmask_b32_e32 v22, v23, v22, vcc
	v_div_scale_f32 v23, s[4:5], v22, v22, 1.0
	v_rcp_f32_e32 v24, v23
	v_div_scale_f32 v25, vcc, 1.0, v22, 1.0
	s_mov_b64 s[4:5], s[24:25]
	v_fma_f32 v26, -v23, v24, 1.0
	v_fmac_f32_e32 v24, v26, v24
	v_mul_f32_e32 v26, v25, v24
	v_fma_f32 v27, -v23, v26, v25
	v_fmac_f32_e32 v26, v27, v24
	v_fma_f32 v23, -v23, v26, v25
	v_div_fmas_f32 v23, v23, v24, v26
	v_div_fixup_f32 v22, v23, v22, 1.0
	v_pk_mul_f32 v[12:13], v[12:13], v[22:23] op_sel_hi:[1,0]
	v_pk_mul_f32 v[14:15], v[14:15], v[22:23] op_sel_hi:[1,0]
	v_pk_mul_f32 v[12:13], v[200:201], v[12:13]
	v_pk_mul_f32 v[14:15], v[202:203], v[14:15]
	global_store_dwordx4 v[20:21], v[12:15], off
	v_pk_mul_f32 v[10:11], v[10:11], v[22:23] op_sel_hi:[1,0]
	v_pk_mul_f32 v[8:9], v[8:9], v[22:23] op_sel_hi:[1,0]
	v_pk_mul_f32 v[6:7], v[6:7], v[22:23] op_sel_hi:[1,0]
	v_pk_mul_f32 v[4:5], v[4:5], v[22:23] op_sel_hi:[1,0]
	v_pk_mul_f32 v[2:3], v[2:3], v[22:23] op_sel_hi:[1,0]
	v_pk_mul_f32 v[0:1], v[0:1], v[22:23] op_sel_hi:[1,0]
	s_and_b64 vcc, exec, s[26:27]
	v_pk_mul_f32 v[8:9], v[204:205], v[8:9]
	v_pk_mul_f32 v[10:11], v[206:207], v[10:11]
	global_store_dwordx4 v[20:21], v[8:11], off offset:64
	v_pk_mul_f32 v[4:5], v[208:209], v[4:5]
	v_pk_mul_f32 v[6:7], v[210:211], v[6:7]
	global_store_dwordx4 v[20:21], v[4:7], off offset:512
	v_pk_mul_f32 v[0:1], v[212:213], v[0:1]
	v_pk_mul_f32 v[2:3], v[214:215], v[2:3]
	global_store_dwordx4 v[20:21], v[0:3], off offset:576
	s_cbranch_vccnz .LBB0_1196
